# static wave priority + GLA prep gate loop hand-scheduled + 16-lane butterfly sums via DPP instead of ds_bpermute (GLA output norm, attention K-norm) + thin GEMM early K loads
# speedup vs baseline: 1.0134x; 1.0087x over previous
; #define LAS __attribute__((address_space(3)))
; __device__ __forceinline__ bf16* st_ptr(unsigned char* ws, int pu) { return (bf16*)(ws + (pu < 392 ? WS_ST0 + (size_t)pu * 262144 : WS_ST1 + (size_t)(pu - 392) * 262144)); }
; __device__ __forceinline__ void gla_out_unit(const Params& P, LAS unsigned char* lds, int u) {
;     ...
;     const int ch = u & 63, h = (u >> 6) & 3, b = u >> 8, tok0 = b * SEQ + ch * 64;
;     unsigned char* ws = P.ws;
;     const bf16* PROJ = (const bf16*)(ws + WS_PROJ); const bf16* QT = (const bf16*)(ws + WS_QT); const bf16* AM = (const bf16*)(ws + WS_AM); const bf16* VT = (const bf16*)(ws + WS_VT);
;     bf16* OB = (bf16*)(ws + WS_OB); const bf16* ST = st_ptr(ws, u);
;     LAS bf16* QS = (LAS bf16*)lds;
;     LAS bf16* AS = (LAS bf16*)(lds + 33792);
;     LAS float* SS = (LAS float*)(lds + 33792 + 9216);
;     LAS float* RS = (LAS float*)(lds + 33792 + 9216 + 2048);
; #pragma unroll
;     for (int it = 0; it < 4; ++it) { const int idx = it * NTHREADS + tid, t = idx >> 5, cc = idx & 31; *(LAS v4u*)(QS + t * 264 + 8 * cc) = *(const v4u*)(QT + ((size_t)u * 64 + t) * 256 + 8 * cc); }
;     { const int t = tid >> 3, cc = tid & 7; *(LAS v4u*)(AS + t * 72 + 8 * cc) = *(const v4u*)(AM + ((size_t)u * 64 + t) * 64 + 8 * cc); }
;     LAS bf16* RT = (LAS bf16*)(lds + 49152);
; #pragma unroll
;     for (int it = 0; it < 8; ++it) { const int idx = it * NTHREADS + tid, t = idx >> 6, cc = idx & 63; const v4u rv = *(const v4u*)(PROJ + (size_t)(tok0 + t) * LD0 + 4096 + 512 * h + 8 * cc);
;         LAS v2u* d = (LAS v2u*)(RT + t * 516 + 8 * cc); d[0] = (v2u){rv.x, rv.y}; d[1] = (v2u){rv.z, rv.w}; }
;     __syncthreads();
.LBB0_485:
	s_and_b32 s4, s13, 0xfc0
	s_add_i32 s0, s6, 0xfffffe78
	s_ashr_i32 s7, s6, 31
	s_cmpk_lt_i32 s6, 0x188
	s_cselect_b32 s3, s7, 0
	s_cselect_b32 s2, s6, s0
	s_mov_b32 s0, 0x9200000
	s_cselect_b32 s0, s0, 0x1b800000
	s_lshl_b64 s[2:3], s[2:3], 18
	s_add_u32 s1, s90, s2
	v_mov_b32_e32 v79, v172
	s_addc_u32 s2, s91, s3
	s_lshl_b64 s[26:27], s[6:7], 15
	s_add_u32 s26, s59, s26
	v_lshlrev_b32_e32 v53, 4, v79
	v_add_u32_e32 v81, 0x400, v79
	s_addc_u32 s27, s60, s27
	v_and_b32_e32 v68, 0x1f0, v53
	v_ashrrev_i32_e32 v54, 5, v79
	v_add_u32_e32 v82, 0x200, v79
	v_ashrrev_i32_e32 v58, 5, v81
	s_and_b32 s3, s12, 0xfffff000
	v_ashrrev_i32_e32 v20, 3, v79
	v_lshl_add_u64 v[12:13], s[26:27], 0, v[68:69]
	v_ashrrev_i32_e32 v55, 31, v54
	v_ashrrev_i32_e32 v56, 5, v82
	v_ashrrev_i32_e32 v59, 31, v58
	v_add_u32_e32 v80, 0x600, v79
	s_or_b32 s25, s3, s4
	v_ashrrev_i32_e32 v21, 31, v20
	s_lshl_b64 s[26:27], s[6:7], 13
	s_movk_i32 s3, 0x90
	v_add_u32_e32 v52, 0, v68
	v_lshlrev_b64 v[0:1], 9, v[54:55]
	v_ashrrev_i32_e32 v57, 31, v56
	v_lshlrev_b64 v[8:9], 9, v[58:59]
	v_ashrrev_i32_e32 v60, 5, v80
	s_add_u32 s26, s61, s26
	v_lshlrev_b64 v[16:17], 7, v[20:21]
	v_and_b32_e32 v68, 0x70, v53
	v_mul_lo_u32 v20, v20, s3
	v_ashrrev_i32_e32 v59, 6, v79
	v_lshl_add_u64 v[0:1], v[12:13], 0, v[0:1]
	v_lshlrev_b64 v[4:5], 9, v[56:57]
	v_ashrrev_i32_e32 v61, 31, v60
	s_addc_u32 s27, s62, s27
	v_add3_u32 v57, 0, v20, v68
	s_and_b32 s3, s24, 0x600
	v_add_u32_e32 v20, s25, v59
	global_load_dwordx4 v[0:3], v[0:1], off
	v_lshl_add_u64 v[4:5], v[12:13], 0, v[4:5]
	v_lshlrev_b64 v[14:15], 9, v[60:61]
	v_lshl_add_u64 v[16:17], s[26:27], 0, v[16:17]
	v_mad_i64_i32 v[20:21], s[26:27], v20, s18, v[70:71]
	s_lshl_b32 s4, s3, 1
	v_ashrrev_i32_e32 v61, 6, v82
	global_load_dwordx4 v[4:7], v[4:5], off
	v_lshl_add_u64 v[8:9], v[12:13], 0, v[8:9]
	v_lshl_add_u64 v[16:17], v[16:17], 0, v[68:69]
	v_and_b32_e32 v68, 0x3f0, v53
	v_lshl_add_u64 v[20:21], v[20:21], 0, s[4:5]
	v_add_u32_e32 v24, s25, v61
	global_load_dwordx4 v[8:11], v[8:9], off
	v_lshl_add_u64 v[12:13], v[12:13], 0, v[14:15]
	v_lshl_add_u64 v[20:21], v[20:21], 0, v[68:69]
	v_mad_i64_i32 v[24:25], s[26:27], v24, s18, v[70:71]
	v_ashrrev_i32_e32 v62, 6, v81
	global_load_dwordx4 v[12:15], v[12:13], off
	v_add_co_u32_e32 v20, vcc, s19, v20
	v_lshl_add_u64 v[24:25], v[24:25], 0, s[4:5]
	v_add_u32_e32 v28, s25, v62
	v_addc_co_u32_e32 v21, vcc, 0, v21, vcc
	v_lshl_add_u64 v[24:25], v[24:25], 0, v[68:69]
	v_mad_i64_i32 v[28:29], s[26:27], v28, s18, v[70:71]
	v_ashrrev_i32_e32 v63, 6, v80
	global_load_dwordx4 v[16:19], v[16:17], off
	v_add_co_u32_e32 v24, vcc, s19, v24
	global_load_dwordx4 v[20:23], v[20:21], off
	v_lshl_add_u64 v[28:29], v[28:29], 0, s[4:5]
	v_add_u32_e32 v32, s25, v63
	v_add_u32_e32 v83, 0x800, v79
	v_addc_co_u32_e32 v25, vcc, 0, v25, vcc
	v_lshl_add_u64 v[28:29], v[28:29], 0, v[68:69]
	v_mad_i64_i32 v[32:33], s[26:27], v32, s18, v[70:71]
	v_ashrrev_i32_e32 v64, 6, v83
	global_load_dwordx4 v[24:27], v[24:25], off
	v_add_co_u32_e32 v28, vcc, s19, v28
	v_lshl_add_u64 v[32:33], v[32:33], 0, s[4:5]
	v_add_u32_e32 v36, s25, v64
	v_add_u32_e32 v86, 0xa00, v79
	v_addc_co_u32_e32 v29, vcc, 0, v29, vcc
	v_lshl_add_u64 v[32:33], v[32:33], 0, v[68:69]
	v_mad_i64_i32 v[36:37], s[26:27], v36, s18, v[70:71]
	v_ashrrev_i32_e32 v65, 6, v86
	global_load_dwordx4 v[28:31], v[28:29], off
	v_add_co_u32_e32 v32, vcc, s19, v32
	v_lshl_add_u64 v[36:37], v[36:37], 0, s[4:5]
	v_add_u32_e32 v40, s25, v65
	v_add_u32_e32 v85, 0xc00, v79
	v_addc_co_u32_e32 v33, vcc, 0, v33, vcc
	v_lshl_add_u64 v[36:37], v[36:37], 0, v[68:69]
	v_mad_i64_i32 v[40:41], s[26:27], v40, s18, v[70:71]
	v_ashrrev_i32_e32 v66, 6, v85
	global_load_dwordx4 v[32:35], v[32:33], off
	v_add_co_u32_e32 v36, vcc, s19, v36
	v_lshl_add_u64 v[40:41], v[40:41], 0, s[4:5]
	v_add_u32_e32 v44, s25, v66
	v_add_u32_e32 v84, 0xe00, v79
	v_addc_co_u32_e32 v37, vcc, 0, v37, vcc
	v_lshl_add_u64 v[40:41], v[40:41], 0, v[68:69]
	v_mad_i64_i32 v[44:45], s[26:27], v44, s18, v[70:71]
	v_ashrrev_i32_e32 v67, 6, v84
	global_load_dwordx4 v[36:39], v[36:37], off
	v_add_co_u32_e32 v40, vcc, s19, v40
	v_lshl_add_u64 v[44:45], v[44:45], 0, s[4:5]
	v_add_u32_e32 v48, s25, v67
	v_addc_co_u32_e32 v41, vcc, 0, v41, vcc
	v_lshl_add_u64 v[44:45], v[44:45], 0, v[68:69]
	v_mad_i64_i32 v[48:49], s[26:27], v48, s18, v[70:71]
	global_load_dwordx4 v[40:43], v[40:41], off
	v_add_co_u32_e32 v44, vcc, s19, v44
	v_lshl_add_u64 v[48:49], v[48:49], 0, s[4:5]
	s_nop 0
	v_addc_co_u32_e32 v45, vcc, 0, v45, vcc
	v_lshl_add_u64 v[48:49], v[48:49], 0, v[68:69]
	global_load_dwordx4 v[44:47], v[44:45], off
	v_add_co_u32_e32 v48, vcc, s19, v48
	v_mad_u64_u32 v[54:55], s[26:27], v54, s17, v[52:53]
	s_nop 0
	v_addc_co_u32_e32 v49, vcc, 0, v49, vcc
	global_load_dwordx4 v[48:51], v[48:49], off
	s_waitcnt vmcnt(12)
	ds_write_b128 v54, v[0:3]
	v_mad_u64_u32 v[0:1], s[26:27], v56, s17, v[52:53]
	s_waitcnt vmcnt(11)
	ds_write_b128 v0, v[4:7]
	v_mad_u64_u32 v[0:1], s[26:27], v58, s17, v[52:53]
	s_waitcnt vmcnt(10)
	ds_write_b128 v0, v[8:11]
	v_mad_u64_u32 v[0:1], s[26:27], v60, s17, v[52:53]
	s_waitcnt vmcnt(9)
	ds_write_b128 v0, v[12:15]
	v_add_u32_e32 v0, 0, v68
	v_mul_lo_u32 v1, v59, s20
	v_add3_u32 v1, v0, v1, s21
	s_waitcnt vmcnt(8)
	ds_write_b128 v57, v[16:19] offset:33792
	s_waitcnt vmcnt(7)
	ds_write2_b64 v1, v[20:21], v[22:23] offset1:1
	v_mul_lo_u32 v1, v61, s20
	v_add3_u32 v1, v0, v1, s21
	v_and_b32_e32 v72, 0xffffffc0, v79
	v_and_b32_e32 v68, 0x200, v53
	s_waitcnt vmcnt(6)
	ds_write2_b64 v1, v[24:25], v[26:27] offset1:1
	v_mul_lo_u32 v1, v62, s20
	v_add3_u32 v1, v0, v1, s21
	v_ashrrev_i32_e32 v73, 31, v72
	v_and_b32_e32 v91, 15, v79
	s_add_u32 s0, s1, s0
	s_addc_u32 s1, s2, 0
	v_bfe_u32 v92, v79, 4, 2
	s_waitcnt vmcnt(5)
	ds_write2_b64 v1, v[28:29], v[30:31] offset1:1
	v_mul_lo_u32 v1, v63, s20
	v_add3_u32 v1, v0, v1, s21
	s_waitcnt vmcnt(4)
	ds_write2_b64 v1, v[32:33], v[34:35] offset1:1
	v_mul_lo_u32 v1, v64, s20
	v_add3_u32 v1, v0, v1, s21
	s_waitcnt vmcnt(3)
	ds_write2_b64 v1, v[36:37], v[38:39] offset1:1
	v_mul_lo_u32 v1, v65, s20
	v_add3_u32 v1, v0, v1, s21
	s_waitcnt vmcnt(2)
	ds_write2_b64 v1, v[40:41], v[42:43] offset1:1
	v_mul_lo_u32 v1, v66, s20
	v_add3_u32 v1, v0, v1, s21
	s_waitcnt vmcnt(1)
	ds_write2_b64 v1, v[44:45], v[46:47] offset1:1
	v_mul_lo_u32 v1, v67, s20
	v_add3_u32 v0, v0, v1, s21
	s_waitcnt vmcnt(0)
	ds_write2_b64 v0, v[48:49], v[50:51] offset1:1
	v_lshl_add_u64 v[0:1], v[68:69], 0, v[72:73]
	v_or_b32_e32 v0, v0, v91
	v_lshlrev_b64 v[0:1], 5, v[0:1]
	v_lshl_add_u64 v[0:1], s[0:1], 0, v[0:1]
	v_and_b32_e32 v68, 16, v79
	v_lshl_add_u64 v[16:17], v[0:1], 0, v[68:69]
	s_waitcnt lgkmcnt(0)
	s_barrier
; #define LAS __attribute__((address_space(3)))
; __device__ __forceinline__ void gla_out_unit(const Params& P, LAS unsigned char* lds, int u) {
;     ...
;     const bf16* stp = ST + ((size_t)(q4 >> 1) * 512 + 64 * wave + fr) * 16 + 8 * (q4 & 1); const bf16* vtp = VT + ((size_t)u * 512 + 64 * wave + fr) * 64 + 8 * q4;
; #pragma unroll
;     for (int kb = 0; kb < 10; ++kb) { bf16x8 bfr[4], afr[4];
; #pragma unroll
;         for (int j = 0; j < 4; ++j) bfr[j] = kb < 8 ? __builtin_nontemporal_load((const bf16x8*)(stp + (size_t)(2 * kb) * 8192 + 16 * j * 16)) : *(const bf16x8*)(vtp + (size_t)(16 * j) * 64 + 32 * (kb - 8));
; #pragma unroll
;         for (int m = 0; m < 4; ++m) afr[m] = kb < 8 ? *(const LAS bf16x8*)(QS + (16 * m + fr) * 264 + 32 * kb + 8 * q4) : *(const LAS bf16x8*)(AS + (16 * m + fr) * 72 + 32 * (kb - 8) + 8 * q4);
; #pragma unroll
;         for (int m = 0; m < 4; ++m)
; #pragma unroll
;             for (int j = 0; j < 4; ++j) acc[m][j] = __builtin_amdgcn_mfma_f32_16x16x32_bf16(afr[m], bfr[j], acc[m][j], 0, 0, 0); }
	global_load_dwordx4 v[0:3], v[16:17], off
	global_load_dwordx4 v[8:11], v[16:17], off offset:512
	global_load_dwordx4 v[12:15], v[16:17], off offset:1024
	global_load_dwordx4 v[32:35], v[16:17], off offset:1536
	v_lshlrev_b32_e32 v68, 4, v92
	v_add_u32_e32 v87, 0, v68
	v_mad_u32_u24 v18, v91, s17, v87
	ds_read_b128 v[4:7], v18
	ds_read_b128 v[98:101], v18 offset:25344
	s_waitcnt vmcnt(3) lgkmcnt(1)
	v_mfma_f32_16x16x32_bf16 v[20:23], v[4:7], v[0:3], 0
	s_mov_b32 s0, 0x8000
	v_add_co_u32_e32 v88, vcc, s0, v16
	s_waitcnt vmcnt(2)
	v_mfma_f32_16x16x32_bf16 v[24:27], v[4:7], v[8:11], 0
	v_addc_co_u32_e32 v89, vcc, 0, v17, vcc
	global_load_dwordx4 v[102:105], v[88:89], off
	s_waitcnt vmcnt(2)
	v_mfma_f32_16x16x32_bf16 v[28:31], v[4:7], v[12:15], 0
	global_load_dwordx4 v[106:109], v[88:89], off offset:1024
	global_load_dwordx4 v[110:113], v[88:89], off offset:1536
	ds_read_b128 v[114:117], v18 offset:25792
	s_waitcnt vmcnt(3)
	v_mfma_f32_16x16x32_bf16 v[36:39], v[4:7], v[32:35], 0
	ds_read_b128 v[4:7], v18 offset:8448
	s_mov_b32 s0, 0x10000
	s_waitcnt lgkmcnt(0)
	v_mfma_f32_16x16x32_bf16 v[40:43], v[4:7], v[0:3], 0
	v_mfma_f32_16x16x32_bf16 v[44:47], v[4:7], v[8:11], 0
	v_mfma_f32_16x16x32_bf16 v[48:51], v[4:7], v[12:15], 0
	v_mfma_f32_16x16x32_bf16 v[52:55], v[4:7], v[32:35], 0
	ds_read_b128 v[4:7], v18 offset:16896
	s_waitcnt lgkmcnt(0)
	v_mfma_f32_16x16x32_bf16 v[56:59], v[4:7], v[0:3], 0
	v_mfma_f32_16x16x32_bf16 v[60:63], v[4:7], v[8:11], 0
	v_mfma_f32_16x16x32_bf16 v[64:67], v[4:7], v[12:15], 0
	v_mfma_f32_16x16x32_bf16 v[94:97], v[4:7], v[32:35], 0
	v_mfma_f32_16x16x32_bf16 v[4:7], v[98:101], v[0:3], 0
	v_mfma_f32_16x16x32_bf16 v[8:11], v[98:101], v[8:11], 0
	v_mfma_f32_16x16x32_bf16 v[12:15], v[98:101], v[12:15], 0
	v_mfma_f32_16x16x32_bf16 v[0:3], v[98:101], v[32:35], 0
	global_load_dwordx4 v[98:101], v[88:89], off offset:512
	ds_read_b128 v[32:35], v18 offset:64
	v_add_co_u32_e32 v88, vcc, s0, v16
	s_waitcnt vmcnt(3) lgkmcnt(0)
	v_mfma_f32_16x16x32_bf16 v[20:23], v[32:35], v[102:105], v[20:23]
	v_addc_co_u32_e32 v89, vcc, 0, v17, vcc
	s_mov_b32 s0, 0x18000
	s_waitcnt vmcnt(0)
	v_mfma_f32_16x16x32_bf16 v[24:27], v[32:35], v[98:101], v[24:27]
	v_mfma_f32_16x16x32_bf16 v[28:31], v[32:35], v[106:109], v[28:31]
	v_mfma_f32_16x16x32_bf16 v[32:35], v[32:35], v[110:113], v[36:39]
	s_nop 2
	ds_read_b128 v[36:39], v18 offset:8512
	s_waitcnt lgkmcnt(0)
	v_mfma_f32_16x16x32_bf16 v[40:43], v[36:39], v[102:105], v[40:43]
	v_mfma_f32_16x16x32_bf16 v[44:47], v[36:39], v[98:101], v[44:47]
	v_mfma_f32_16x16x32_bf16 v[48:51], v[36:39], v[106:109], v[48:51]
	v_mfma_f32_16x16x32_bf16 v[36:39], v[36:39], v[110:113], v[52:55]
	s_nop 2
	ds_read_b128 v[52:55], v18 offset:16960
	s_waitcnt lgkmcnt(0)
	v_mfma_f32_16x16x32_bf16 v[56:59], v[52:55], v[102:105], v[56:59]
	v_mfma_f32_16x16x32_bf16 v[60:63], v[52:55], v[98:101], v[60:63]
	v_mfma_f32_16x16x32_bf16 v[64:67], v[52:55], v[106:109], v[64:67]
	v_mfma_f32_16x16x32_bf16 v[52:55], v[52:55], v[110:113], v[94:97]
	s_nop 2
	ds_read_b128 v[94:97], v18 offset:25408
	s_waitcnt lgkmcnt(0)
	v_mfma_f32_16x16x32_bf16 v[4:7], v[94:97], v[102:105], v[4:7]
	global_load_dwordx4 v[102:105], v[88:89], off offset:512
	v_mfma_f32_16x16x32_bf16 v[8:11], v[94:97], v[98:101], v[8:11]
	global_load_dwordx4 v[98:101], v[88:89], off
	v_mfma_f32_16x16x32_bf16 v[12:15], v[94:97], v[106:109], v[12:15]
	global_load_dwordx4 v[106:109], v[88:89], off offset:1024
	v_mfma_f32_16x16x32_bf16 v[0:3], v[94:97], v[110:113], v[0:3]
	global_load_dwordx4 v[110:113], v[88:89], off offset:1536
	ds_read_b128 v[94:97], v18 offset:128
	v_add_co_u32_e32 v88, vcc, s0, v16
	s_waitcnt vmcnt(2) lgkmcnt(0)
	v_mfma_f32_16x16x32_bf16 v[20:23], v[94:97], v[98:101], v[20:23]
	v_addc_co_u32_e32 v89, vcc, 0, v17, vcc
	s_mov_b32 s0, 0x20000
	v_mfma_f32_16x16x32_bf16 v[24:27], v[94:97], v[102:105], v[24:27]
	s_waitcnt vmcnt(1)
	v_mfma_f32_16x16x32_bf16 v[28:31], v[94:97], v[106:109], v[28:31]
	s_waitcnt vmcnt(0)
	v_mfma_f32_16x16x32_bf16 v[32:35], v[94:97], v[110:113], v[32:35]
	ds_read_b128 v[94:97], v18 offset:8576
	s_waitcnt lgkmcnt(0)
	v_mfma_f32_16x16x32_bf16 v[40:43], v[94:97], v[98:101], v[40:43]
	v_mfma_f32_16x16x32_bf16 v[44:47], v[94:97], v[102:105], v[44:47]
	v_mfma_f32_16x16x32_bf16 v[48:51], v[94:97], v[106:109], v[48:51]
	v_mfma_f32_16x16x32_bf16 v[36:39], v[94:97], v[110:113], v[36:39]
	ds_read_b128 v[94:97], v18 offset:17024
	s_waitcnt lgkmcnt(0)
	v_mfma_f32_16x16x32_bf16 v[56:59], v[94:97], v[98:101], v[56:59]
	v_mfma_f32_16x16x32_bf16 v[60:63], v[94:97], v[102:105], v[60:63]
	v_mfma_f32_16x16x32_bf16 v[64:67], v[94:97], v[106:109], v[64:67]
	v_mfma_f32_16x16x32_bf16 v[52:55], v[94:97], v[110:113], v[52:55]
	ds_read_b128 v[94:97], v18 offset:25472
	s_waitcnt lgkmcnt(0)
	v_mfma_f32_16x16x32_bf16 v[4:7], v[94:97], v[98:101], v[4:7]
	global_load_dwordx4 v[98:101], v[88:89], off
	v_mfma_f32_16x16x32_bf16 v[8:11], v[94:97], v[102:105], v[8:11]
	global_load_dwordx4 v[102:105], v[88:89], off offset:512
	v_mfma_f32_16x16x32_bf16 v[12:15], v[94:97], v[106:109], v[12:15]
	global_load_dwordx4 v[106:109], v[88:89], off offset:1024
	v_mfma_f32_16x16x32_bf16 v[0:3], v[94:97], v[110:113], v[0:3]
	global_load_dwordx4 v[110:113], v[88:89], off offset:1536
	ds_read_b128 v[94:97], v18 offset:192
	v_add_co_u32_e32 v88, vcc, s0, v16
	s_waitcnt vmcnt(3) lgkmcnt(0)
	v_mfma_f32_16x16x32_bf16 v[20:23], v[94:97], v[98:101], v[20:23]
	v_addc_co_u32_e32 v89, vcc, 0, v17, vcc
	s_mov_b32 s0, 0x28000
	s_waitcnt vmcnt(2)
	v_mfma_f32_16x16x32_bf16 v[24:27], v[94:97], v[102:105], v[24:27]
	s_waitcnt vmcnt(1)
	v_mfma_f32_16x16x32_bf16 v[28:31], v[94:97], v[106:109], v[28:31]
	s_waitcnt vmcnt(0)
; #define LAS __attribute__((address_space(3)))
; __device__ __forceinline__ void gla_out_unit(const Params& P, LAS unsigned char* lds, int u) {
;     ...
;     const bf16* stp = ST + ((size_t)(q4 >> 1) * 512 + 64 * wave + fr) * 16 + 8 * (q4 & 1); const bf16* vtp = VT + ((size_t)u * 512 + 64 * wave + fr) * 64 + 8 * q4;
; #pragma unroll
;     for (int kb = 0; kb < 10; ++kb) { bf16x8 bfr[4], afr[4];
; #pragma unroll
;         for (int j = 0; j < 4; ++j) bfr[j] = kb < 8 ? __builtin_nontemporal_load((const bf16x8*)(stp + (size_t)(2 * kb) * 8192 + 16 * j * 16)) : *(const bf16x8*)(vtp + (size_t)(16 * j) * 64 + 32 * (kb - 8));
; #pragma unroll
;         for (int m = 0; m < 4; ++m) afr[m] = kb < 8 ? *(const LAS bf16x8*)(QS + (16 * m + fr) * 264 + 32 * kb + 8 * q4) : *(const LAS bf16x8*)(AS + (16 * m + fr) * 72 + 32 * (kb - 8) + 8 * q4);
; #pragma unroll
;         for (int m = 0; m < 4; ++m)
; #pragma unroll
;             for (int j = 0; j < 4; ++j) acc[m][j] = __builtin_amdgcn_mfma_f32_16x16x32_bf16(afr[m], bfr[j], acc[m][j], 0, 0, 0); }
	v_mfma_f32_16x16x32_bf16 v[32:35], v[94:97], v[110:113], v[32:35]
	ds_read_b128 v[94:97], v18 offset:8640
	s_waitcnt lgkmcnt(0)
	v_mfma_f32_16x16x32_bf16 v[40:43], v[94:97], v[98:101], v[40:43]
	v_mfma_f32_16x16x32_bf16 v[44:47], v[94:97], v[102:105], v[44:47]
	v_mfma_f32_16x16x32_bf16 v[48:51], v[94:97], v[106:109], v[48:51]
	v_mfma_f32_16x16x32_bf16 v[36:39], v[94:97], v[110:113], v[36:39]
	ds_read_b128 v[94:97], v18 offset:17088
	s_waitcnt lgkmcnt(0)
	v_mfma_f32_16x16x32_bf16 v[56:59], v[94:97], v[98:101], v[56:59]
	v_mfma_f32_16x16x32_bf16 v[60:63], v[94:97], v[102:105], v[60:63]
	v_mfma_f32_16x16x32_bf16 v[64:67], v[94:97], v[106:109], v[64:67]
	v_mfma_f32_16x16x32_bf16 v[52:55], v[94:97], v[110:113], v[52:55]
	ds_read_b128 v[94:97], v18 offset:25536
	s_waitcnt lgkmcnt(0)
	v_mfma_f32_16x16x32_bf16 v[4:7], v[94:97], v[98:101], v[4:7]
	global_load_dwordx4 v[98:101], v[88:89], off
	v_mfma_f32_16x16x32_bf16 v[8:11], v[94:97], v[102:105], v[8:11]
	global_load_dwordx4 v[102:105], v[88:89], off offset:512
	v_mfma_f32_16x16x32_bf16 v[12:15], v[94:97], v[106:109], v[12:15]
	global_load_dwordx4 v[106:109], v[88:89], off offset:1024
	v_mfma_f32_16x16x32_bf16 v[0:3], v[94:97], v[110:113], v[0:3]
	global_load_dwordx4 v[110:113], v[88:89], off offset:1536
	ds_read_b128 v[94:97], v18 offset:256
	v_add_co_u32_e32 v88, vcc, s0, v16
	s_waitcnt vmcnt(3) lgkmcnt(0)
	v_mfma_f32_16x16x32_bf16 v[20:23], v[94:97], v[98:101], v[20:23]
	v_addc_co_u32_e32 v89, vcc, 0, v17, vcc
	s_mov_b32 s0, 0x30000
	s_waitcnt vmcnt(2)
	v_mfma_f32_16x16x32_bf16 v[24:27], v[94:97], v[102:105], v[24:27]
	s_waitcnt vmcnt(1)
	v_mfma_f32_16x16x32_bf16 v[28:31], v[94:97], v[106:109], v[28:31]
	s_waitcnt vmcnt(0)
	v_mfma_f32_16x16x32_bf16 v[32:35], v[94:97], v[110:113], v[32:35]
	ds_read_b128 v[94:97], v18 offset:8704
	s_waitcnt lgkmcnt(0)
	v_mfma_f32_16x16x32_bf16 v[40:43], v[94:97], v[98:101], v[40:43]
	v_mfma_f32_16x16x32_bf16 v[44:47], v[94:97], v[102:105], v[44:47]
	v_mfma_f32_16x16x32_bf16 v[48:51], v[94:97], v[106:109], v[48:51]
	v_mfma_f32_16x16x32_bf16 v[36:39], v[94:97], v[110:113], v[36:39]
	ds_read_b128 v[94:97], v18 offset:17152
	s_waitcnt lgkmcnt(0)
	v_mfma_f32_16x16x32_bf16 v[56:59], v[94:97], v[98:101], v[56:59]
	v_mfma_f32_16x16x32_bf16 v[60:63], v[94:97], v[102:105], v[60:63]
	v_mfma_f32_16x16x32_bf16 v[64:67], v[94:97], v[106:109], v[64:67]
	v_mfma_f32_16x16x32_bf16 v[52:55], v[94:97], v[110:113], v[52:55]
	ds_read_b128 v[94:97], v18 offset:25600
	s_waitcnt lgkmcnt(0)
	v_mfma_f32_16x16x32_bf16 v[4:7], v[94:97], v[98:101], v[4:7]
	global_load_dwordx4 v[98:101], v[88:89], off
	v_mfma_f32_16x16x32_bf16 v[8:11], v[94:97], v[102:105], v[8:11]
	global_load_dwordx4 v[102:105], v[88:89], off offset:512
	v_mfma_f32_16x16x32_bf16 v[12:15], v[94:97], v[106:109], v[12:15]
	global_load_dwordx4 v[106:109], v[88:89], off offset:1024
	v_mfma_f32_16x16x32_bf16 v[0:3], v[94:97], v[110:113], v[0:3]
	global_load_dwordx4 v[110:113], v[88:89], off offset:1536
	ds_read_b128 v[94:97], v18 offset:320
	v_add_co_u32_e32 v88, vcc, s0, v16
	s_waitcnt vmcnt(3) lgkmcnt(0)
	v_mfma_f32_16x16x32_bf16 v[20:23], v[94:97], v[98:101], v[20:23]
	v_addc_co_u32_e32 v89, vcc, 0, v17, vcc
	s_mov_b32 s0, 0x38000
	s_waitcnt vmcnt(2)
	v_mfma_f32_16x16x32_bf16 v[24:27], v[94:97], v[102:105], v[24:27]
	v_add_co_u32_e32 v16, vcc, s0, v16
	s_lshl_b64 s[0:1], s[6:7], 9
	s_waitcnt vmcnt(1)
	v_mfma_f32_16x16x32_bf16 v[28:31], v[94:97], v[106:109], v[28:31]
	v_addc_co_u32_e32 v17, vcc, 0, v17, vcc
	s_waitcnt vmcnt(0)
	v_mfma_f32_16x16x32_bf16 v[32:35], v[94:97], v[110:113], v[32:35]
	ds_read_b128 v[94:97], v18 offset:8768
	s_waitcnt lgkmcnt(0)
	v_mfma_f32_16x16x32_bf16 v[40:43], v[94:97], v[98:101], v[40:43]
	v_mfma_f32_16x16x32_bf16 v[44:47], v[94:97], v[102:105], v[44:47]
	v_mfma_f32_16x16x32_bf16 v[48:51], v[94:97], v[106:109], v[48:51]
	v_mfma_f32_16x16x32_bf16 v[36:39], v[94:97], v[110:113], v[36:39]
	ds_read_b128 v[94:97], v18 offset:17216
	s_waitcnt lgkmcnt(0)
	v_mfma_f32_16x16x32_bf16 v[56:59], v[94:97], v[98:101], v[56:59]
	v_mfma_f32_16x16x32_bf16 v[60:63], v[94:97], v[102:105], v[60:63]
	v_mfma_f32_16x16x32_bf16 v[64:67], v[94:97], v[106:109], v[64:67]
	v_mfma_f32_16x16x32_bf16 v[52:55], v[94:97], v[110:113], v[52:55]
	ds_read_b128 v[94:97], v18 offset:25664
	s_waitcnt lgkmcnt(0)
	v_mfma_f32_16x16x32_bf16 v[4:7], v[94:97], v[98:101], v[4:7]
	global_load_dwordx4 v[98:101], v[88:89], off
	v_mfma_f32_16x16x32_bf16 v[8:11], v[94:97], v[102:105], v[8:11]
	global_load_dwordx4 v[102:105], v[88:89], off offset:512
	v_mfma_f32_16x16x32_bf16 v[12:15], v[94:97], v[106:109], v[12:15]
	global_load_dwordx4 v[106:109], v[88:89], off offset:1024
	v_mfma_f32_16x16x32_bf16 v[0:3], v[94:97], v[110:113], v[0:3]
	global_load_dwordx4 v[110:113], v[88:89], off offset:1536
	ds_read_b128 v[94:97], v18 offset:384
	s_waitcnt vmcnt(3) lgkmcnt(0)
	v_mfma_f32_16x16x32_bf16 v[20:23], v[94:97], v[98:101], v[20:23]
	s_waitcnt vmcnt(2)
	v_mfma_f32_16x16x32_bf16 v[24:27], v[94:97], v[102:105], v[24:27]
	s_waitcnt vmcnt(1)
	v_mfma_f32_16x16x32_bf16 v[28:31], v[94:97], v[106:109], v[28:31]
	s_waitcnt vmcnt(0)
	v_mfma_f32_16x16x32_bf16 v[32:35], v[94:97], v[110:113], v[32:35]
	ds_read_b128 v[94:97], v18 offset:8832
	s_waitcnt lgkmcnt(0)
	v_mfma_f32_16x16x32_bf16 v[40:43], v[94:97], v[98:101], v[40:43]
	v_mfma_f32_16x16x32_bf16 v[44:47], v[94:97], v[102:105], v[44:47]
	v_mfma_f32_16x16x32_bf16 v[48:51], v[94:97], v[106:109], v[48:51]
	v_mfma_f32_16x16x32_bf16 v[36:39], v[94:97], v[110:113], v[36:39]
	ds_read_b128 v[94:97], v18 offset:17280
	s_waitcnt lgkmcnt(0)
; #define LAS __attribute__((address_space(3)))
; __device__ __forceinline__ void gla_out_unit(const Params& P, LAS unsigned char* lds, int u) {
;     ...
;     for (int kb = 0; kb < 10; ++kb) { bf16x8 bfr[4], afr[4];
; #pragma unroll
;         for (int j = 0; j < 4; ++j) bfr[j] = kb < 8 ? __builtin_nontemporal_load((const bf16x8*)(stp + (size_t)(2 * kb) * 8192 + 16 * j * 16)) : *(const bf16x8*)(vtp + (size_t)(16 * j) * 64 + 32 * (kb - 8));
; #pragma unroll
;         for (int m = 0; m < 4; ++m) afr[m] = kb < 8 ? *(const LAS bf16x8*)(QS + (16 * m + fr) * 264 + 32 * kb + 8 * q4) : *(const LAS bf16x8*)(AS + (16 * m + fr) * 72 + 32 * (kb - 8) + 8 * q4);
; #pragma unroll
;         for (int m = 0; m < 4; ++m)
; #pragma unroll
;             for (int j = 0; j < 4; ++j) acc[m][j] = __builtin_amdgcn_mfma_f32_16x16x32_bf16(afr[m], bfr[j], acc[m][j], 0, 0, 0); }
; #pragma unroll
;     for (int m = 0; m < 4; ++m)
; #pragma unroll
;         for (int i = 0; i < 4; ++i) { float s = 0.f;
; #pragma unroll
;             for (int j = 0; j < 4; ++j) s += acc[m][j][i] * acc[m][j][i];
;             s += __shfl_xor(s, 1); s += __shfl_xor(s, 2); s += __shfl_xor(s, 4); s += __shfl_xor(s, 8);
;             if (fr == 0) SS[wave * 64 + 16 * m + 4 * q4 + i] = s; }
	v_mfma_f32_16x16x32_bf16 v[56:59], v[94:97], v[98:101], v[56:59]
	v_mfma_f32_16x16x32_bf16 v[60:63], v[94:97], v[102:105], v[60:63]
	v_mfma_f32_16x16x32_bf16 v[64:67], v[94:97], v[106:109], v[64:67]
	v_mfma_f32_16x16x32_bf16 v[52:55], v[94:97], v[110:113], v[52:55]
	ds_read_b128 v[94:97], v18 offset:25728
	s_waitcnt lgkmcnt(0)
	v_mfma_f32_16x16x32_bf16 v[98:101], v[94:97], v[98:101], v[4:7]
	v_mfma_f32_16x16x32_bf16 v[8:11], v[94:97], v[102:105], v[8:11]
	global_load_dwordx4 v[102:105], v[16:17], off offset:512
	v_mfma_f32_16x16x32_bf16 v[4:7], v[94:97], v[106:109], v[12:15]
	global_load_dwordx4 v[106:109], v[16:17], off offset:1024
	s_nop 1
	global_load_dwordx4 v[12:15], v[16:17], off
	v_mfma_f32_16x16x32_bf16 v[0:3], v[94:97], v[110:113], v[0:3]
	global_load_dwordx4 v[110:113], v[16:17], off offset:1536
	ds_read_b128 v[94:97], v18 offset:448
	v_lshl_add_u64 v[16:17], s[0:1], 0, v[72:73]
	s_waitcnt vmcnt(1) lgkmcnt(0)
	v_mfma_f32_16x16x32_bf16 v[20:23], v[94:97], v[12:15], v[20:23]
	v_or_b32_e32 v16, v16, v91
	v_lshlrev_b64 v[16:17], 7, v[16:17]
	v_lshl_add_u64 v[16:17], s[90:91], 0, v[16:17]
	v_mfma_f32_16x16x32_bf16 v[24:27], v[94:97], v[102:105], v[24:27]
	v_lshl_add_u64 v[16:17], v[16:17], 0, v[68:69]
	s_mov_b32 s0, 0x17401000
	v_add_co_u32_e32 v88, vcc, s0, v16
	v_mfma_f32_16x16x32_bf16 v[28:31], v[94:97], v[106:109], v[28:31]
	s_nop 0
	v_addc_co_u32_e32 v89, vcc, 0, v17, vcc
	s_mov_b32 s0, 0x17400000
	s_waitcnt vmcnt(0)
	v_mfma_f32_16x16x32_bf16 v[32:35], v[94:97], v[110:113], v[32:35]
	ds_read_b128 v[94:97], v18 offset:8896
	v_add_co_u32_e32 v126, vcc, s0, v16
	s_waitcnt lgkmcnt(0)
	v_mfma_f32_16x16x32_bf16 v[40:43], v[94:97], v[12:15], v[40:43]
	v_addc_co_u32_e32 v127, vcc, 0, v17, vcc
	v_mad_i32_i24 v68, v91, s22, v18
	v_mfma_f32_16x16x32_bf16 v[44:47], v[94:97], v[102:105], v[44:47]
	v_cmp_lt_i32_e32 vcc, v176, v177
	v_mfma_f32_16x16x32_bf16 v[48:51], v[94:97], v[106:109], v[48:51]
	v_mfma_f32_16x16x32_bf16 v[36:39], v[94:97], v[110:113], v[36:39]
	ds_read_b128 v[94:97], v18 offset:17344
	s_waitcnt lgkmcnt(0)
	v_mfma_f32_16x16x32_bf16 v[56:59], v[94:97], v[12:15], v[56:59]
	v_mfma_f32_16x16x32_bf16 v[60:63], v[94:97], v[102:105], v[60:63]
	v_mfma_f32_16x16x32_bf16 v[64:67], v[94:97], v[106:109], v[64:67]
	v_mfma_f32_16x16x32_bf16 v[52:55], v[94:97], v[110:113], v[52:55]
	global_load_dwordx4 v[94:97], v[88:89], off offset:-4096
	v_mfma_f32_16x16x32_bf16 v[12:15], v[114:117], v[12:15], v[98:101]
	v_mfma_f32_16x16x32_bf16 v[8:11], v[114:117], v[102:105], v[8:11]
	global_load_dwordx4 v[102:105], v[126:127], off offset:2048
	v_mfma_f32_16x16x32_bf16 v[98:101], v[114:117], v[106:109], v[4:7]
	global_load_dwordx4 v[106:109], v[88:89], off
	v_mfma_f32_16x16x32_bf16 v[0:3], v[114:117], v[110:113], v[0:3]
	global_load_dwordx4 v[114:117], v[88:89], off offset:2048
	ds_read_b128 v[4:7], v68 offset:33792
	s_waitcnt vmcnt(3) lgkmcnt(0)
	v_mfma_f32_16x16x32_bf16 v[20:23], v[4:7], v[94:97], v[20:23]
	s_waitcnt vmcnt(2)
	v_mfma_f32_16x16x32_bf16 v[24:27], v[4:7], v[102:105], v[24:27]
	s_waitcnt vmcnt(1)
	v_mfma_f32_16x16x32_bf16 v[110:113], v[4:7], v[106:109], v[28:31]
	s_waitcnt vmcnt(0)
	v_mfma_f32_16x16x32_bf16 v[32:35], v[4:7], v[114:117], v[32:35]
	ds_read_b128 v[4:7], v68 offset:36096
	s_waitcnt lgkmcnt(0)
	v_mfma_f32_16x16x32_bf16 v[40:43], v[4:7], v[94:97], v[40:43]
	v_mfma_f32_16x16x32_bf16 v[118:121], v[4:7], v[102:105], v[44:47]
	v_mfma_f32_16x16x32_bf16 v[122:125], v[4:7], v[106:109], v[48:51]
	v_mfma_f32_16x16x32_bf16 v[130:133], v[4:7], v[114:117], v[36:39]
	ds_read_b128 v[4:7], v68 offset:38400
	s_nop 1
	ds_read_b128 v[36:39], v68 offset:40704
	s_waitcnt lgkmcnt(1)
	v_mfma_f32_16x16x32_bf16 v[28:31], v[4:7], v[106:109], v[64:67]
	s_nop 2
	global_load_dwordx4 v[64:67], v[126:127], off offset:64
	v_mfma_f32_16x16x32_bf16 v[134:137], v[4:7], v[94:97], v[56:59]
	s_waitcnt lgkmcnt(0)
	v_mfma_f32_16x16x32_bf16 v[12:15], v[36:39], v[94:97], v[12:15]
	global_load_dwordx4 v[94:97], v[126:127], off offset:2112
	v_mfma_f32_16x16x32_bf16 v[138:141], v[4:7], v[102:105], v[60:63]
	v_mfma_f32_16x16x32_bf16 v[16:19], v[4:7], v[114:117], v[52:55]
	v_mfma_f32_16x16x32_bf16 v[4:7], v[36:39], v[102:105], v[8:11]
	global_load_dwordx4 v[102:105], v[88:89], off offset:2112
	v_mfma_f32_16x16x32_bf16 v[8:11], v[36:39], v[106:109], v[98:101]
	s_nop 2
	global_load_dwordx4 v[98:101], v[88:89], off offset:64
	v_mfma_f32_16x16x32_bf16 v[0:3], v[36:39], v[114:117], v[0:3]
	ds_read_b128 v[36:39], v68 offset:33856
	s_waitcnt vmcnt(3) lgkmcnt(0)
	v_mfma_f32_16x16x32_bf16 v[56:59], v[36:39], v[64:67], v[20:23]
	s_nop 2
	ds_read_b128 v[20:23], v68 offset:36160
	s_waitcnt vmcnt(2)
	v_mfma_f32_16x16x32_bf16 v[52:55], v[36:39], v[94:97], v[24:27]
	s_waitcnt vmcnt(0)
	v_mfma_f32_16x16x32_bf16 v[60:63], v[36:39], v[98:101], v[110:113]
	s_nop 5
	v_mul_f32_e32 v88, v52, v52
	v_fmac_f32_e32 v88, v56, v56
	ds_read_b128 v[106:109], v68 offset:38464
	ds_read_b128 v[110:113], v68 offset:40768
	v_mfma_f32_16x16x32_bf16 v[48:51], v[36:39], v[102:105], v[32:35]
	v_fmac_f32_e32 v88, v60, v60
	s_waitcnt lgkmcnt(2)
	v_mfma_f32_16x16x32_bf16 v[44:47], v[20:23], v[64:67], v[40:43]
	v_mfma_f32_16x16x32_bf16 v[40:43], v[20:23], v[94:97], v[118:121]
	s_nop 3
	v_fmac_f32_e32 v88, v48, v48
	v_mfma_f32_16x16x32_bf16 v[36:39], v[20:23], v[98:101], v[122:125]
	v_mfma_f32_16x16x32_bf16 v[32:35], v[20:23], v[102:105], v[130:133]
	v_cndmask_b32_e32 v20, v175, v176, vcc
	v_lshlrev_b32_e32 v68, 2, v20
	v_cmp_lt_i32_e32 vcc, v74, v177
	s_waitcnt lgkmcnt(1)
	v_mfma_f32_16x16x32_bf16 v[20:23], v[106:109], v[64:67], v[134:137]
	s_waitcnt lgkmcnt(0)
	v_add_f32_dpp v88, v88, v88 quad_perm:[1,0,3,2] row_mask:0xf bank_mask:0xf
	v_cndmask_b32_e32 v73, v175, v74, vcc
	v_lshlrev_b32_e32 v73, 2, v73
	v_cmp_lt_i32_e32 vcc, v75, v177
	v_mfma_f32_16x16x32_bf16 v[12:15], v[110:113], v[64:67], v[12:15]
	s_waitcnt lgkmcnt(0)
	v_add_f32_dpp v67, v88, v88 quad_perm:[2,3,0,1] row_mask:0xf bank_mask:0xf
	v_cndmask_b32_e32 v90, v175, v75, vcc
	v_lshlrev_b32_e32 v64, 2, v90
	v_cmp_lt_i32_e32 vcc, v76, v177
	v_mfma_f32_16x16x32_bf16 v[24:27], v[106:109], v[94:97], v[138:141]
	s_waitcnt lgkmcnt(0)
	v_add_f32_dpp v67, v67, v67 row_half_mirror row_mask:0xf bank_mask:0xf
	v_cndmask_b32_e32 v65, v175, v76, vcc
	v_lshlrev_b32_e32 v66, 2, v65
	v_add_f32_dpp v67, v67, v67 row_mirror row_mask:0xf bank_mask:0xf
	v_mfma_f32_16x16x32_bf16 v[28:31], v[106:109], v[98:101], v[28:31]
	v_cmp_eq_u32_e32 vcc, 0, v91
	v_lshl_add_u32 v65, v72, 2, v87
	v_mfma_f32_16x16x32_bf16 v[16:19], v[106:109], v[102:105], v[16:19]
	v_mfma_f32_16x16x32_bf16 v[4:7], v[110:113], v[94:97], v[4:7]
	v_mfma_f32_16x16x32_bf16 v[8:11], v[110:113], v[98:101], v[8:11]
	v_mfma_f32_16x16x32_bf16 v[0:3], v[110:113], v[102:105], v[0:3]
	s_and_saveexec_b64 s[0:1], vcc
	s_cbranch_execz .LBB0_487
	s_waitcnt lgkmcnt(0)
	ds_write_b32 v65, v67 offset:43008
; __device__ __forceinline__ void gla_out_unit(const Params& P, LAS unsigned char* lds, int u) {
;     ...
;     for (int m = 0; m < 4; ++m)
; #pragma unroll
;         for (int i = 0; i < 4; ++i) { float s = 0.f;
; #pragma unroll
;             for (int j = 0; j < 4; ++j) s += acc[m][j][i] * acc[m][j][i];
;             s += __shfl_xor(s, 1); s += __shfl_xor(s, 2); s += __shfl_xor(s, 4); s += __shfl_xor(s, 8);
;             if (fr == 0) SS[wave * 64 + 16 * m + 4 * q4 + i] = s; }
.LBB0_487:
	s_or_b64 exec, exec, s[0:1]
	v_mul_f32_e32 v67, v53, v53
	v_fmac_f32_e32 v67, v57, v57
	v_fmac_f32_e32 v67, v61, v61
	v_fmac_f32_e32 v67, v49, v49
	s_waitcnt lgkmcnt(0)
	s_waitcnt lgkmcnt(0)
	v_add_f32_dpp v67, v67, v67 quad_perm:[1,0,3,2] row_mask:0xf bank_mask:0xf
	s_waitcnt lgkmcnt(0)
	s_nop 0
	v_add_f32_dpp v67, v67, v67 quad_perm:[2,3,0,1] row_mask:0xf bank_mask:0xf
	s_waitcnt lgkmcnt(0)
	s_nop 0
	v_add_f32_dpp v67, v67, v67 row_half_mirror row_mask:0xf bank_mask:0xf
	s_nop 1
	v_add_f32_dpp v67, v67, v67 row_mirror row_mask:0xf bank_mask:0xf
	s_and_saveexec_b64 s[0:1], vcc
	s_cbranch_execz .LBB0_489
	s_waitcnt lgkmcnt(0)
	ds_write_b32 v65, v67 offset:43012
.LBB0_489:
	s_or_b64 exec, exec, s[0:1]
	v_mul_f32_e32 v67, v54, v54
	v_fmac_f32_e32 v67, v58, v58
	v_fmac_f32_e32 v67, v62, v62
	v_fmac_f32_e32 v67, v50, v50
	s_waitcnt lgkmcnt(0)
	s_waitcnt lgkmcnt(0)
	v_add_f32_dpp v67, v67, v67 quad_perm:[1,0,3,2] row_mask:0xf bank_mask:0xf
	s_waitcnt lgkmcnt(0)
	s_nop 0
	v_add_f32_dpp v67, v67, v67 quad_perm:[2,3,0,1] row_mask:0xf bank_mask:0xf
	s_waitcnt lgkmcnt(0)
	s_nop 0
	v_add_f32_dpp v67, v67, v67 row_half_mirror row_mask:0xf bank_mask:0xf
	s_nop 1
	v_add_f32_dpp v67, v67, v67 row_mirror row_mask:0xf bank_mask:0xf
	s_and_saveexec_b64 s[0:1], vcc
	s_cbranch_execz .LBB0_491
	s_waitcnt lgkmcnt(0)
	ds_write_b32 v65, v67 offset:43016
.LBB0_491:
	s_or_b64 exec, exec, s[0:1]
	v_mul_f32_e32 v67, v55, v55
	v_fmac_f32_e32 v67, v59, v59
	v_fmac_f32_e32 v67, v63, v63
	v_fmac_f32_e32 v67, v51, v51
	s_waitcnt lgkmcnt(0)
	s_waitcnt lgkmcnt(0)
	v_add_f32_dpp v67, v67, v67 quad_perm:[1,0,3,2] row_mask:0xf bank_mask:0xf
	s_waitcnt lgkmcnt(0)
	s_nop 0
	v_add_f32_dpp v67, v67, v67 quad_perm:[2,3,0,1] row_mask:0xf bank_mask:0xf
	s_waitcnt lgkmcnt(0)
	s_nop 0
	v_add_f32_dpp v67, v67, v67 row_half_mirror row_mask:0xf bank_mask:0xf
	s_nop 1
	v_add_f32_dpp v67, v67, v67 row_mirror row_mask:0xf bank_mask:0xf
	s_and_saveexec_b64 s[0:1], vcc
	s_cbranch_execz .LBB0_493
	s_waitcnt lgkmcnt(0)
	ds_write_b32 v65, v67 offset:43020
.LBB0_493:
	s_or_b64 exec, exec, s[0:1]
	v_mul_f32_e32 v67, v40, v40
	v_fmac_f32_e32 v67, v44, v44
	v_fmac_f32_e32 v67, v36, v36
	v_fmac_f32_e32 v67, v32, v32
	s_waitcnt lgkmcnt(0)
	s_waitcnt lgkmcnt(0)
	v_add_f32_dpp v67, v67, v67 quad_perm:[1,0,3,2] row_mask:0xf bank_mask:0xf
	s_waitcnt lgkmcnt(0)
	s_nop 0
	v_add_f32_dpp v67, v67, v67 quad_perm:[2,3,0,1] row_mask:0xf bank_mask:0xf
	s_waitcnt lgkmcnt(0)
	s_nop 0
	v_add_f32_dpp v67, v67, v67 row_half_mirror row_mask:0xf bank_mask:0xf
	s_nop 1
	v_add_f32_dpp v67, v67, v67 row_mirror row_mask:0xf bank_mask:0xf
	s_and_saveexec_b64 s[0:1], vcc
	s_cbranch_execz .LBB0_495
	s_waitcnt lgkmcnt(0)
	ds_write_b32 v65, v67 offset:43072
.LBB0_495:
	s_or_b64 exec, exec, s[0:1]
	v_mul_f32_e32 v67, v41, v41
	v_fmac_f32_e32 v67, v45, v45
	v_fmac_f32_e32 v67, v37, v37
	v_fmac_f32_e32 v67, v33, v33
	s_waitcnt lgkmcnt(0)
	s_waitcnt lgkmcnt(0)
	v_add_f32_dpp v67, v67, v67 quad_perm:[1,0,3,2] row_mask:0xf bank_mask:0xf
	s_waitcnt lgkmcnt(0)
	s_nop 0
	v_add_f32_dpp v67, v67, v67 quad_perm:[2,3,0,1] row_mask:0xf bank_mask:0xf
	s_waitcnt lgkmcnt(0)
	s_nop 0
	v_add_f32_dpp v67, v67, v67 row_half_mirror row_mask:0xf bank_mask:0xf
	s_nop 1
	v_add_f32_dpp v67, v67, v67 row_mirror row_mask:0xf bank_mask:0xf
	s_and_saveexec_b64 s[0:1], vcc
	s_cbranch_execz .LBB0_497
	s_waitcnt lgkmcnt(0)
	ds_write_b32 v65, v67 offset:43076
.LBB0_497:
	s_or_b64 exec, exec, s[0:1]
	v_mul_f32_e32 v67, v42, v42
	v_fmac_f32_e32 v67, v46, v46
	v_fmac_f32_e32 v67, v38, v38
	v_fmac_f32_e32 v67, v34, v34
	s_waitcnt lgkmcnt(0)
	s_waitcnt lgkmcnt(0)
	v_add_f32_dpp v67, v67, v67 quad_perm:[1,0,3,2] row_mask:0xf bank_mask:0xf
	s_waitcnt lgkmcnt(0)
	s_nop 0
	v_add_f32_dpp v67, v67, v67 quad_perm:[2,3,0,1] row_mask:0xf bank_mask:0xf
	s_waitcnt lgkmcnt(0)
	s_nop 0
	v_add_f32_dpp v67, v67, v67 row_half_mirror row_mask:0xf bank_mask:0xf
	s_nop 1
	v_add_f32_dpp v67, v67, v67 row_mirror row_mask:0xf bank_mask:0xf
	s_and_saveexec_b64 s[0:1], vcc
	s_cbranch_execz .LBB0_499
	s_waitcnt lgkmcnt(0)
	ds_write_b32 v65, v67 offset:43080
.LBB0_499:
	s_or_b64 exec, exec, s[0:1]
	v_mul_f32_e32 v67, v43, v43
	v_fmac_f32_e32 v67, v47, v47
	v_fmac_f32_e32 v67, v39, v39
	v_fmac_f32_e32 v67, v35, v35
	s_waitcnt lgkmcnt(0)
	s_waitcnt lgkmcnt(0)
	v_add_f32_dpp v67, v67, v67 quad_perm:[1,0,3,2] row_mask:0xf bank_mask:0xf
	s_waitcnt lgkmcnt(0)
	s_nop 0
	v_add_f32_dpp v67, v67, v67 quad_perm:[2,3,0,1] row_mask:0xf bank_mask:0xf
	s_waitcnt lgkmcnt(0)
	s_nop 0
	v_add_f32_dpp v67, v67, v67 row_half_mirror row_mask:0xf bank_mask:0xf
	s_nop 1
	v_add_f32_dpp v67, v67, v67 row_mirror row_mask:0xf bank_mask:0xf
	s_and_saveexec_b64 s[0:1], vcc
	s_cbranch_execz .LBB0_501
	s_waitcnt lgkmcnt(0)
	ds_write_b32 v65, v67 offset:43084
; __device__ __forceinline__ void gla_out_unit(const Params& P, LAS unsigned char* lds, int u) {
;     ...
;     for (int m = 0; m < 4; ++m)
; #pragma unroll
;         for (int i = 0; i < 4; ++i) { float s = 0.f;
; #pragma unroll
;             for (int j = 0; j < 4; ++j) s += acc[m][j][i] * acc[m][j][i];
;             s += __shfl_xor(s, 1); s += __shfl_xor(s, 2); s += __shfl_xor(s, 4); s += __shfl_xor(s, 8);
;             if (fr == 0) SS[wave * 64 + 16 * m + 4 * q4 + i] = s; }
.LBB0_501:
	s_or_b64 exec, exec, s[0:1]
	v_mul_f32_e32 v67, v24, v24
	v_fmac_f32_e32 v67, v20, v20
	v_fmac_f32_e32 v67, v28, v28
	v_fmac_f32_e32 v67, v16, v16
	s_waitcnt lgkmcnt(0)
	s_waitcnt lgkmcnt(0)
	v_add_f32_dpp v67, v67, v67 quad_perm:[1,0,3,2] row_mask:0xf bank_mask:0xf
	s_waitcnt lgkmcnt(0)
	s_nop 0
	v_add_f32_dpp v67, v67, v67 quad_perm:[2,3,0,1] row_mask:0xf bank_mask:0xf
	s_waitcnt lgkmcnt(0)
	s_nop 0
	v_add_f32_dpp v67, v67, v67 row_half_mirror row_mask:0xf bank_mask:0xf
	s_nop 1
	v_add_f32_dpp v67, v67, v67 row_mirror row_mask:0xf bank_mask:0xf
	s_and_saveexec_b64 s[0:1], vcc
	s_cbranch_execz .LBB0_503
	s_waitcnt lgkmcnt(0)
	ds_write_b32 v65, v67 offset:43136
.LBB0_503:
	s_or_b64 exec, exec, s[0:1]
	v_mul_f32_e32 v67, v25, v25
	v_fmac_f32_e32 v67, v21, v21
	v_fmac_f32_e32 v67, v29, v29
	v_fmac_f32_e32 v67, v17, v17
	s_waitcnt lgkmcnt(0)
	s_waitcnt lgkmcnt(0)
	v_add_f32_dpp v67, v67, v67 quad_perm:[1,0,3,2] row_mask:0xf bank_mask:0xf
	s_waitcnt lgkmcnt(0)
	s_nop 0
	v_add_f32_dpp v67, v67, v67 quad_perm:[2,3,0,1] row_mask:0xf bank_mask:0xf
	s_waitcnt lgkmcnt(0)
	s_nop 0
	v_add_f32_dpp v67, v67, v67 row_half_mirror row_mask:0xf bank_mask:0xf
	s_nop 1
	v_add_f32_dpp v67, v67, v67 row_mirror row_mask:0xf bank_mask:0xf
	s_and_saveexec_b64 s[0:1], vcc
	s_cbranch_execz .LBB0_505
	s_waitcnt lgkmcnt(0)
	ds_write_b32 v65, v67 offset:43140
.LBB0_505:
	s_or_b64 exec, exec, s[0:1]
	v_mul_f32_e32 v67, v26, v26
	v_fmac_f32_e32 v67, v22, v22
	v_fmac_f32_e32 v67, v30, v30
	v_fmac_f32_e32 v67, v18, v18
	s_waitcnt lgkmcnt(0)
	s_waitcnt lgkmcnt(0)
	v_add_f32_dpp v67, v67, v67 quad_perm:[1,0,3,2] row_mask:0xf bank_mask:0xf
	s_waitcnt lgkmcnt(0)
	s_nop 0
	v_add_f32_dpp v67, v67, v67 quad_perm:[2,3,0,1] row_mask:0xf bank_mask:0xf
	s_waitcnt lgkmcnt(0)
	s_nop 0
	v_add_f32_dpp v67, v67, v67 row_half_mirror row_mask:0xf bank_mask:0xf
	s_nop 1
	v_add_f32_dpp v67, v67, v67 row_mirror row_mask:0xf bank_mask:0xf
	s_and_saveexec_b64 s[0:1], vcc
	s_cbranch_execz .LBB0_507
	s_waitcnt lgkmcnt(0)
	ds_write_b32 v65, v67 offset:43144
.LBB0_507:
	s_or_b64 exec, exec, s[0:1]
	v_mul_f32_e32 v67, v27, v27
	v_fmac_f32_e32 v67, v23, v23
	v_fmac_f32_e32 v67, v31, v31
	v_fmac_f32_e32 v67, v19, v19
	s_waitcnt lgkmcnt(0)
	s_waitcnt lgkmcnt(0)
	v_add_f32_dpp v67, v67, v67 quad_perm:[1,0,3,2] row_mask:0xf bank_mask:0xf
	s_waitcnt lgkmcnt(0)
	s_nop 0
	v_add_f32_dpp v67, v67, v67 quad_perm:[2,3,0,1] row_mask:0xf bank_mask:0xf
	s_waitcnt lgkmcnt(0)
	s_nop 0
	v_add_f32_dpp v67, v67, v67 row_half_mirror row_mask:0xf bank_mask:0xf
	s_nop 1
	v_add_f32_dpp v67, v67, v67 row_mirror row_mask:0xf bank_mask:0xf
	s_and_saveexec_b64 s[0:1], vcc
	s_cbranch_execz .LBB0_509
	s_waitcnt lgkmcnt(0)
	ds_write_b32 v65, v67 offset:43148
.LBB0_509:
	s_or_b64 exec, exec, s[0:1]
	v_mul_f32_e32 v67, v4, v4
	v_fmac_f32_e32 v67, v12, v12
	v_fmac_f32_e32 v67, v8, v8
	v_fmac_f32_e32 v67, v0, v0
	s_waitcnt lgkmcnt(0)
	s_waitcnt lgkmcnt(0)
	v_add_f32_dpp v67, v67, v67 quad_perm:[1,0,3,2] row_mask:0xf bank_mask:0xf
	s_waitcnt lgkmcnt(0)
	s_nop 0
	v_add_f32_dpp v67, v67, v67 quad_perm:[2,3,0,1] row_mask:0xf bank_mask:0xf
	s_waitcnt lgkmcnt(0)
	s_nop 0
	v_add_f32_dpp v67, v67, v67 row_half_mirror row_mask:0xf bank_mask:0xf
	s_nop 1
	v_add_f32_dpp v67, v67, v67 row_mirror row_mask:0xf bank_mask:0xf
	s_and_saveexec_b64 s[0:1], vcc
	s_cbranch_execz .LBB0_511
	s_waitcnt lgkmcnt(0)
	ds_write_b32 v65, v67 offset:43200
.LBB0_511:
	s_or_b64 exec, exec, s[0:1]
	v_mul_f32_e32 v67, v5, v5
	v_fmac_f32_e32 v67, v13, v13
	v_fmac_f32_e32 v67, v9, v9
	v_fmac_f32_e32 v67, v1, v1
	s_waitcnt lgkmcnt(0)
	s_waitcnt lgkmcnt(0)
	v_add_f32_dpp v67, v67, v67 quad_perm:[1,0,3,2] row_mask:0xf bank_mask:0xf
	s_waitcnt lgkmcnt(0)
	s_nop 0
	v_add_f32_dpp v67, v67, v67 quad_perm:[2,3,0,1] row_mask:0xf bank_mask:0xf
	s_waitcnt lgkmcnt(0)
	s_nop 0
	v_add_f32_dpp v67, v67, v67 row_half_mirror row_mask:0xf bank_mask:0xf
	s_nop 1
	v_add_f32_dpp v67, v67, v67 row_mirror row_mask:0xf bank_mask:0xf
	s_and_saveexec_b64 s[0:1], vcc
	s_cbranch_execz .LBB0_513
	s_waitcnt lgkmcnt(0)
	ds_write_b32 v65, v67 offset:43204
.LBB0_513:
	s_or_b64 exec, exec, s[0:1]
	v_mul_f32_e32 v67, v6, v6
	v_fmac_f32_e32 v67, v14, v14
	v_fmac_f32_e32 v67, v10, v10
	v_fmac_f32_e32 v67, v2, v2
	s_waitcnt lgkmcnt(0)
	s_waitcnt lgkmcnt(0)
	v_add_f32_dpp v67, v67, v67 quad_perm:[1,0,3,2] row_mask:0xf bank_mask:0xf
	s_waitcnt lgkmcnt(0)
	s_nop 0
	v_add_f32_dpp v67, v67, v67 quad_perm:[2,3,0,1] row_mask:0xf bank_mask:0xf
	s_waitcnt lgkmcnt(0)
	s_nop 0
	v_add_f32_dpp v67, v67, v67 row_half_mirror row_mask:0xf bank_mask:0xf
	s_nop 1
	v_add_f32_dpp v67, v67, v67 row_mirror row_mask:0xf bank_mask:0xf
	s_and_saveexec_b64 s[0:1], vcc
	s_cbranch_execz .LBB0_515
	s_waitcnt lgkmcnt(0)
	ds_write_b32 v65, v67 offset:43208
.LBB0_515:
	s_or_b64 exec, exec, s[0:1]
	v_mul_f32_e32 v67, v7, v7
	v_fmac_f32_e32 v67, v15, v15
	v_fmac_f32_e32 v67, v11, v11
	v_fmac_f32_e32 v67, v3, v3
	s_waitcnt lgkmcnt(0)
	s_nop 0
	v_add_f32_dpp v67, v67, v67 quad_perm:[1,0,3,2] row_mask:0xf bank_mask:0xf
	s_waitcnt lgkmcnt(0)
	s_nop 0
	v_add_f32_dpp v67, v67, v67 quad_perm:[2,3,0,1] row_mask:0xf bank_mask:0xf
	s_waitcnt lgkmcnt(0)
	s_nop 0
	v_add_f32_dpp v64, v67, v67 row_half_mirror row_mask:0xf bank_mask:0xf
	s_nop 1
	v_add_f32_dpp v64, v64, v64 row_mirror row_mask:0xf bank_mask:0xf
	s_and_saveexec_b64 s[0:1], vcc
	s_cbranch_execz .LBB0_517
	s_waitcnt lgkmcnt(0)
	ds_write_b32 v65, v64 offset:43212

; __device__ __forceinline__ unsigned cvtpk(float lo, float hi) { f32x2_t v = {lo, hi}; bf16x2_t b = __builtin_convertvector(v, bf16x2_t); return __builtin_bit_cast(unsigned, b); }
; __device__ __forceinline__ int v_st(int k, int c) { const int kk = (k & ~0xC) | ((k & 4) << 1) | ((k & 8) >> 1); return ((kk >> 3) * 4 + (c >> 5)) * 512 + ((kk & 7) * 32 + (c & 31)) * 2; }
; __device__ __forceinline__ int v_rd_base(int lane) { return ((lane & 3) << 3) | (((lane >> 2) & 3) << 6) | (((lane >> 4) & 1) << 5) | (((lane >> 5) & 1) << 8); }
; __device__ __forceinline__ bf16x8 knorm8(bf16x8 x, const float* g) {
;     const v4u xv = __builtin_bit_cast(v4u, x); float f[8];
; #pragma unroll
;     for (int e = 0; e < 4; ++e) { f[2 * e] = __builtin_bit_cast(float, xv[e] << 16); f[2 * e + 1] = __builtin_bit_cast(float, xv[e] & 0xffff0000u); }
;     float s = 0.f;
; #pragma unroll
;     for (int e = 0; e < 8; ++e) s += f[e] * f[e];
;     s += __shfl_xor(s, 1); s += __shfl_xor(s, 2); s += __shfl_xor(s, 4); s += __shfl_xor(s, 8);
;     const float r = __builtin_amdgcn_rsqf(s * (1.0f / 128.0f) + 1e-6f);
;     const f32x4 g0 = *(const f32x4*)g, g1 = *(const f32x4*)(g + 4);
;     v4u w; w.x = cvtpk(f[0] * r * g0[0], f[1] * r * g0[1]); w.y = cvtpk(f[2] * r * g0[2], f[3] * r * g0[3]); w.z = cvtpk(f[4] * r * g1[0], f[5] * r * g1[1]); w.w = cvtpk(f[6] * r * g1[2], f[7] * r * g1[3]);
;     return __builtin_bit_cast(bf16x8, w);
; __device__ __forceinline__ void fox_attn_unit(const Params& P, char* lds, int b, int h, int qb) {
;     ...
;     const int sr = tid >> 4, sc = (tid & 15) * 8, vst0 = v_st(sr, sc), vst1 = v_st(32 + sr, sc), kws = KSWZ(sr, sc * 2);
;     const int vb0 = (int)(uintptr_t)V_lds + v_rd_base(lane);
;     const int NT = 4 * (qb + 1);
;     bf16x8 st_k0, st_k1, st_v0, st_v1;
;     for (int i = tid; i < (q0 + 256) / 4; i += NTHREADS) ((f32x4*)ckl)[i] = ((const f32x4*)CF)[i];
;     ...
;     float m_reg = -1e30f, l_reg = 0.f; f32x16 o[4] = {};
;     __syncthreads();
;     int j_lo; { const float thr = *(const float*)(ws + WS_THR), cq0 = ckl[q0];
;         const bool skip = lane < 4 * qb && ckl[64 * lane + 63] - cq0 > thr; const unsigned long long bm = __ballot(!skip); j_lo = (int)__builtin_ctzll(bm) & ~1; }
;     SLOAD(NT - 1); SWRITE(0);
.LBB0_1332:
	s_or_b64 exec, exec, s[2:3]
	v_ashrrev_i32_e32 v77, 4, v114
	v_and_b32_e32 v1, 0xfffff0, v77
	v_lshlrev_b32_e32 v2, 1, v77
	v_lshlrev_b32_e32 v0, 3, v114
	v_and_or_b32 v1, v2, 8, v1
	s_and_b32 s2, s7, 15
	v_and_b32_e32 v16, 0x78, v0
	v_lshrrev_b32_e32 v2, 1, v77
	v_lshrrev_b32_e32 v1, 1, v1
	v_bfe_u32 v0, v0, 5, 2
	v_and_b32_e32 v3, 3, v77
	s_lshl_b32 s2, s2, 8
	v_or_b32_e32 v1, v1, v0
	v_and_or_b32 v2, v2, 4, v3
	v_lshlrev_b32_e32 v3, 1, v16
	v_writelane_b32 v236, s2, 36
	s_and_b32 s2, s6, 0x3fffffc0
	v_lshlrev_b32_e32 v1, 9, v1
	v_lshlrev_b32_e32 v2, 6, v2
	v_and_b32_e32 v4, 48, v3
	s_lshl_b32 s2, s2, 2
	v_or3_b32 v20, v1, v2, v4
	v_add_u32_e32 v1, 32, v77
	s_add_i32 s7, s2, 0
	s_mov_b32 s2, s16
	v_and_b32_e32 v5, 0xfffff0, v1
	v_lshlrev_b32_e32 v1, 1, v1
	s_mov_b32 s14, s16
	s_ashr_i32 s15, s16, 31
	v_writelane_b32 v236, s2, 37
	v_and_or_b32 v1, v1, 8, v5
	s_add_i32 s7, s7, 0x14000
	v_writelane_b32 v236, s3, 38
	s_lshl_b64 s[2:3], s[14:15], 14
	v_readlane_b32 s14, v237, 52
	v_lshrrev_b32_e32 v1, 1, v1
	v_readlane_b32 s15, v237, 53
	s_add_u32 s6, s14, s2
	v_or_b32_e32 v0, v1, v0
	s_addc_u32 s9, s15, s3
	s_lshl_b32 s16, s8, 1
	v_lshlrev_b32_e32 v0, 9, v0
	v_writelane_b32 v236, s16, 27
	s_add_u32 s6, s6, s16
	v_or3_b32 v21, v0, v2, v4
	v_lshlrev_b32_e32 v0, 8, v77
	v_and_b32_e32 v1, 0x70, v114
	s_addc_u32 s8, s9, 0
	v_bitop3_b32 v38, v3, v0, v1 bitop3:0xde
	s_add_u32 s74, s6, 0x1000
	v_cndmask_b32_e64 v0, 0, 1, s[0:1]
	s_addc_u32 s75, s8, 0
	v_cmp_ne_u32_e32 vcc, 0, v0
	s_add_u32 s84, s6, 0x2000
	s_ff1_i32_b64 s0, vcc
	s_addc_u32 s85, s8, 0
	s_and_b32 s73, s0, 62
	s_or_b32 s0, s13, 3
	v_lshl_add_u32 v0, s0, 6, v77
	v_ashrrev_i32_e32 v1, 31, v0
	v_lshlrev_b64 v[0:1], 14, v[0:1]
	v_or_b32_e32 v0, v0, v3
	v_lshl_add_u64 v[2:3], s[74:75], 0, v[0:1]
	global_load_dwordx4 v[12:15], v[2:3], off
	s_mov_b32 s1, 0x80000
	v_add_co_u32_e32 v2, vcc, s1, v2
	v_lshl_add_u64 v[4:5], s[84:85], 0, v[0:1]
	s_nop 0
	v_addc_co_u32_e32 v3, vcc, 0, v3, vcc
	global_load_dwordx4 v[8:11], v[2:3], off
	v_lshl_add_u32 v16, v16, 2, 0
	global_load_dwordx4 v[0:3], v[4:5], off
	v_add_co_u32_e32 v4, vcc, s1, v4
	v_add_u32_e32 v153, 0x24800, v16
	s_nop 0
	v_addc_co_u32_e32 v5, vcc, 0, v5, vcc
	global_load_dwordx4 v[4:7], v[4:5], off
	v_cmp_lt_i32_e32 vcc, v176, v177
	v_add_u32_e32 v154, 0, v38
	v_add_u32_e32 v157, 0, v20
	v_cndmask_b32_e32 v16, v175, v176, vcc
	v_lshlrev_b32_e32 v144, 2, v16
	v_xor_b32_e32 v16, 2, v175
	v_cmp_lt_i32_e32 vcc, v16, v177
	v_add_u32_e32 v158, 0, v21
	s_cmp_le_u32 s0, s73
	v_cndmask_b32_e32 v16, v175, v16, vcc
	v_lshlrev_b32_e32 v145, 2, v16
	v_xor_b32_e32 v16, 4, v175
	v_cmp_lt_i32_e32 vcc, v16, v177
	v_lshlrev_b32_e32 v115, 4, v151
	v_cmp_gt_u32_e64 s[8:9], 32, v151
	v_cndmask_b32_e32 v16, v175, v16, vcc
	v_lshlrev_b32_e32 v146, 2, v16
	v_xor_b32_e32 v16, 8, v175
	v_cmp_lt_i32_e32 vcc, v16, v177
	v_lshl_add_u32 v155, v150, 2, s7
	v_mov_b32_e32 v47, 0
	v_cndmask_b32_e32 v16, v175, v16, vcc
	v_lshlrev_b32_e32 v147, 2, v16
	ds_read_b128 v[16:19], v153
	ds_read_b128 v[22:25], v153 offset:16
	v_mov_b32_e32 v46, 0
	v_mov_b32_e32 v45, 0
	v_mov_b32_e32 v44, 0
	v_mov_b32_e32 v43, 0
	v_mov_b32_e32 v42, 0
	v_mov_b32_e32 v41, 0
	v_mov_b32_e32 v40, 0
	v_mov_b32_e32 v39, 0
	v_mov_b32_e32 v38, 0
	v_mov_b32_e32 v63, 0
	v_mov_b32_e32 v62, 0
	v_mov_b32_e32 v61, 0
	v_mov_b32_e32 v60, 0
	v_mov_b32_e32 v59, 0
	v_mov_b32_e32 v58, 0
	v_mov_b32_e32 v57, 0
	v_mov_b32_e32 v56, 0
	v_mov_b32_e32 v55, 0
	v_mov_b32_e32 v54, 0
	v_mov_b32_e32 v53, 0
	v_mov_b32_e32 v52, 0
	v_mov_b32_e32 v51, 0
	v_mov_b32_e32 v50, 0
	v_mov_b32_e32 v49, 0
	v_mov_b32_e32 v48, 0
	v_mov_b32_e32 v21, 0
	v_mov_b32_e32 v20, 0
	v_mov_b32_e32 v156, 0
	v_writelane_b32 v236, s17, 28
	s_waitcnt vmcnt(3)
	v_lshlrev_b32_e32 v36, 16, v12
	v_and_b32_e32 v37, 0xffff0000, v12
	v_lshlrev_b32_e32 v32, 16, v13
	v_and_b32_e32 v33, 0xffff0000, v13
	v_pk_mul_f32 v[12:13], v[36:37], v[36:37]
	v_pk_mul_f32 v[34:35], v[32:33], v[32:33]
	v_add_f32_e32 v12, v12, v13
	v_lshlrev_b32_e32 v30, 16, v14
	v_and_b32_e32 v31, 0xffff0000, v14
	v_add_f32_e32 v12, v34, v12
	v_lshlrev_b32_e32 v26, 16, v15
	v_and_b32_e32 v27, 0xffff0000, v15
	v_pk_mul_f32 v[14:15], v[30:31], v[30:31]
	v_add_f32_e32 v12, v35, v12
	v_add_f32_e32 v12, v14, v12
	v_pk_mul_f32 v[28:29], v[26:27], v[26:27]
	v_add_f32_e32 v12, v15, v12
	v_add_f32_e32 v12, v28, v12
	v_add_f32_e32 v12, v29, v12
	v_mov_b32_e32 v35, 0
	v_mov_b32_e32 v34, 0
	s_waitcnt lgkmcnt(0)
	v_add_f32_dpp v12, v12, v12 quad_perm:[1,0,3,2] row_mask:0xf bank_mask:0xf
	s_waitcnt lgkmcnt(0)
	s_nop 0
	v_add_f32_dpp v12, v12, v12 quad_perm:[2,3,0,1] row_mask:0xf bank_mask:0xf
	s_waitcnt lgkmcnt(0)
	s_nop 0
	v_add_f32_dpp v12, v12, v12 row_half_mirror row_mask:0xf bank_mask:0xf
	s_waitcnt lgkmcnt(0)
	s_nop 0
	v_add_f32_dpp v12, v12, v12 row_mirror row_mask:0xf bank_mask:0xf
	v_fmamk_f32 v12, v12, 0x3c000000, v141
	v_rsq_f32_e32 v28, v12
	s_nop 0
	v_pk_mul_f32 v[12:13], v[28:29], v[36:37] op_sel_hi:[0,1]
	v_pk_mul_f32 v[14:15], v[28:29], v[32:33] op_sel_hi:[0,1]
	v_pk_mul_f32 v[12:13], v[16:17], v[12:13]
	v_pk_mul_f32 v[14:15], v[18:19], v[14:15]
	s_waitcnt vmcnt(2)
; __device__ __forceinline__ unsigned cvtpk(float lo, float hi) { f32x2_t v = {lo, hi}; bf16x2_t b = __builtin_convertvector(v, bf16x2_t); return __builtin_bit_cast(unsigned, b); }
; __device__ __forceinline__ int v_rd_base(int lane) { return ((lane & 3) << 3) | (((lane >> 2) & 3) << 6) | (((lane >> 4) & 1) << 5) | (((lane >> 5) & 1) << 8); }
; #define SLOAD(t) do { const size_t r0_ = (size_t)((t) * 64 + sr) * LD1 + sc; st_k0 = *(const bf16x8*)(Kh + r0_); st_k1 = *(const bf16x8*)(Kh + r0_ + (size_t)32 * LD1); \
;         st_v0 = *(const bf16x8*)(Vh + r0_); st_v1 = *(const bf16x8*)(Vh + r0_ + (size_t)32 * LD1); } while (0)
; __device__ __forceinline__ bf16x8 knorm8(bf16x8 x, const float* g) {
;     const v4u xv = __builtin_bit_cast(v4u, x); float f[8];
; #pragma unroll
;     for (int e = 0; e < 4; ++e) { f[2 * e] = __builtin_bit_cast(float, xv[e] << 16); f[2 * e + 1] = __builtin_bit_cast(float, xv[e] & 0xffff0000u); }
;     float s = 0.f;
; #pragma unroll
;     for (int e = 0; e < 8; ++e) s += f[e] * f[e];
;     s += __shfl_xor(s, 1); s += __shfl_xor(s, 2); s += __shfl_xor(s, 4); s += __shfl_xor(s, 8);
;     const float r = __builtin_amdgcn_rsqf(s * (1.0f / 128.0f) + 1e-6f);
;     const f32x4 g0 = *(const f32x4*)g, g1 = *(const f32x4*)(g + 4);
;     v4u w; w.x = cvtpk(f[0] * r * g0[0], f[1] * r * g0[1]); w.y = cvtpk(f[2] * r * g0[2], f[3] * r * g0[3]); w.z = cvtpk(f[4] * r * g1[0], f[5] * r * g1[1]); w.w = cvtpk(f[6] * r * g1[2], f[7] * r * g1[3]);
;     return __builtin_bit_cast(bf16x8, w);
; __device__ __forceinline__ void fox_attn_unit(const Params& P, char* lds, int b, int h, int qb) {
;     ...
;     const int vb0 = (int)(uintptr_t)V_lds + v_rd_base(lane);
;     const int NT = 4 * (qb + 1);
;     bf16x8 st_k0, st_k1, st_v0, st_v1;
;     for (int i = tid; i < (q0 + 256) / 4; i += NTHREADS) ((f32x4*)ckl)[i] = ((const f32x4*)CF)[i];
;     ...
;     float m_reg = -1e30f, l_reg = 0.f; f32x16 o[4] = {};
;     __syncthreads();
;     int j_lo; { const float thr = *(const float*)(ws + WS_THR), cq0 = ckl[q0];
;         const bool skip = lane < 4 * qb && ckl[64 * lane + 63] - cq0 > thr; const unsigned long long bm = __ballot(!skip); j_lo = (int)__builtin_ctzll(bm) & ~1; }
;     SLOAD(NT - 1); SWRITE(0);
;     __syncthreads();
;     for (int t = NT - 1; t > j_lo; t -= 2) {
	v_lshlrev_b32_e32 v32, 16, v8
	v_and_b32_e32 v33, 0xffff0000, v8
	v_cvt_pk_bf16_f32 v12, v12, v13
	v_cvt_pk_bf16_f32 v13, v14, v15
	v_pk_mul_f32 v[14:15], v[28:29], v[30:31] op_sel_hi:[0,1]
	v_pk_mul_f32 v[16:17], v[28:29], v[26:27] op_sel_hi:[0,1]
	v_lshlrev_b32_e32 v28, 16, v9
	v_and_b32_e32 v29, 0xffff0000, v9
	v_pk_mul_f32 v[8:9], v[32:33], v[32:33]
	v_pk_mul_f32 v[30:31], v[28:29], v[28:29]
	v_add_f32_e32 v8, v8, v9
	v_lshlrev_b32_e32 v26, 16, v10
	v_and_b32_e32 v27, 0xffff0000, v10
	v_add_f32_e32 v8, v30, v8
	v_pk_mul_f32 v[14:15], v[22:23], v[14:15]
	v_lshlrev_b32_e32 v22, 16, v11
	v_and_b32_e32 v23, 0xffff0000, v11
	v_pk_mul_f32 v[10:11], v[26:27], v[26:27]
	v_add_f32_e32 v8, v31, v8
	v_add_f32_e32 v8, v10, v8
	v_pk_mul_f32 v[16:17], v[24:25], v[16:17]
	v_pk_mul_f32 v[24:25], v[22:23], v[22:23]
	v_add_f32_e32 v8, v11, v8
	v_add_f32_e32 v8, v24, v8
	v_add_f32_e32 v8, v25, v8
	v_cvt_pk_bf16_f32 v14, v14, v15
	v_cvt_pk_bf16_f32 v15, v16, v17
	ds_write_b128 v154, v[12:15] offset:32768
	ds_read_b128 v[16:19], v153
	ds_read_b128 v[12:15], v153 offset:16
	s_waitcnt lgkmcnt(3)
	v_add_f32_dpp v8, v8, v8 quad_perm:[1,0,3,2] row_mask:0xf bank_mask:0xf
	v_mov_b32_e32 v37, 0
	v_mov_b32_e32 v36, 0
	v_mov_b32_e32 v31, 0
	v_mov_b32_e32 v30, 0
	s_waitcnt lgkmcnt(0)
	v_add_f32_dpp v8, v8, v8 quad_perm:[2,3,0,1] row_mask:0xf bank_mask:0xf
	s_waitcnt lgkmcnt(0)
	s_nop 0
	v_add_f32_dpp v8, v8, v8 row_half_mirror row_mask:0xf bank_mask:0xf
	s_waitcnt lgkmcnt(0)
	s_nop 0
	v_add_f32_dpp v8, v8, v8 row_mirror row_mask:0xf bank_mask:0xf
	v_fmamk_f32 v8, v8, 0x3c000000, v141
	v_rsq_f32_e32 v24, v8
	s_nop 0
	v_pk_mul_f32 v[8:9], v[24:25], v[32:33] op_sel_hi:[0,1]
	v_pk_mul_f32 v[10:11], v[24:25], v[28:29] op_sel_hi:[0,1]
	v_pk_mul_f32 v[8:9], v[16:17], v[8:9]
	v_pk_mul_f32 v[10:11], v[18:19], v[10:11]
	v_cvt_pk_bf16_f32 v8, v8, v9
	v_cvt_pk_bf16_f32 v9, v10, v11
	v_pk_mul_f32 v[10:11], v[24:25], v[26:27] op_sel_hi:[0,1]
	v_pk_mul_f32 v[10:11], v[12:13], v[10:11]
	v_pk_mul_f32 v[12:13], v[24:25], v[22:23] op_sel_hi:[0,1]
	v_pk_mul_f32 v[12:13], v[14:15], v[12:13]
	v_cvt_pk_bf16_f32 v10, v10, v11
	v_cvt_pk_bf16_f32 v11, v12, v13
	ds_write_b128 v154, v[8:11] offset:40960
	s_waitcnt vmcnt(1)
	ds_write_b128 v157, v[0:3]
	s_waitcnt vmcnt(0)
	ds_write_b128 v158, v[4:7]
	v_mov_b32_e32 v15, 0
	v_mov_b32_e32 v14, 0
	v_mov_b32_e32 v13, 0
	v_mov_b32_e32 v12, 0
	v_mov_b32_e32 v11, 0
	v_mov_b32_e32 v10, 0
	v_mov_b32_e32 v9, 0
	v_mov_b32_e32 v8, 0
	v_mov_b32_e32 v7, 0
	v_mov_b32_e32 v6, 0
	v_mov_b32_e32 v5, 0
	v_mov_b32_e32 v4, 0
	v_mov_b32_e32 v3, 0
	v_mov_b32_e32 v2, 0
	v_mov_b32_e32 v1, 0
	v_mov_b32_e32 v0, 0
	v_mov_b32_e32 v33, 0
	v_mov_b32_e32 v32, 0
	v_mov_b32_e32 v29, 0
	v_mov_b32_e32 v28, 0
	v_mov_b32_e32 v27, 0
	v_mov_b32_e32 v26, 0
	v_mov_b32_e32 v25, 0
	v_mov_b32_e32 v24, 0
	v_mov_b32_e32 v23, 0
	v_mov_b32_e32 v22, 0
	v_mov_b32_e32 v19, 0
	v_mov_b32_e32 v18, 0
	v_mov_b32_e32 v17, 0
	v_mov_b32_e32 v16, 0
	s_waitcnt lgkmcnt(0)
	s_barrier
	s_cbranch_scc1 .LBB0_1352
	v_lshlrev_b32_e32 v0, 3, v151
	v_and_b32_e32 v1, 0xc0, v115
	v_lshlrev_b32_e32 v2, 1, v151
	v_and_or_b32 v1, v0, 24, v1
	v_and_b32_e32 v2, 32, v2
	v_and_b32_e32 v0, 0x100, v0
	s_cmp_lg_u32 0, -1
	v_or3_b32 v0, v1, v2, v0
	s_cselect_b32 s0, 0, 0
	v_add_u32_e32 v159, s0, v0
	v_lshlrev_b32_e32 v0, 4, v150
	v_and_b32_e32 v0, 0x70, v0
	v_or_b32_e32 v1, 32, v78
	v_xad_u32 v4, v1, v0, 0
	v_or_b32_e32 v1, 64, v78
	v_xad_u32 v5, v1, v0, 0
	v_or_b32_e32 v1, 0x60, v78
	s_or_b32 s86, s40, 1
	v_readlane_b32 s0, v236, 36
	v_xad_u32 v3, v78, v0, 0
	v_xad_u32 v6, v1, v0, 0
	v_and_b32_e32 v0, 15, v114
	v_add_u32_e32 v8, s11, v77
	s_add_u32 s0, s90, s0
	v_lshlrev_b32_e32 v112, 4, v0
	v_add_u32_e32 v0, 64, v8
	s_addc_u32 s1, s91, 0
	v_ashrrev_i32_e32 v1, 31, v0
	s_add_u32 s0, s0, s2
	v_lshlrev_b64 v[0:1], 14, v[0:1]
	s_addc_u32 s1, s1, s3
	s_addk_i32 s12, 0xff40
	v_lshlrev_b32_e32 v7, 2, v149
	v_lshl_add_u64 v[116:117], s[0:1], 0, v[0:1]
	v_add_u32_e32 v0, s12, v150
	v_sub_u32_e32 v161, v0, v7
	v_add_u32_e32 v0, 0x80, v8
	s_lshl_b32 s10, s10, 10
	v_ashrrev_i32_e32 v1, 31, v0
	v_lshlrev_b32_e32 v2, 8, v150
	s_add_i32 s10, s10, 0
	v_lshlrev_b64 v[0:1], 14, v[0:1]
	v_mov_b32_e32 v16, v113
	v_mov_b32_e32 v17, v113
	v_mov_b32_e32 v30, v113
	v_mov_b32_e32 v31, v113
	s_add_i32 s10, s10, 0x10200
	v_lshl_add_u64 v[118:119], s[0:1], 0, v[0:1]
	v_mov_b32_e32 v18, v113
	v_mov_b32_e32 v19, v113
	v_mov_b32_e32 v20, v113
	v_mov_b32_e32 v21, v113
	v_mov_b32_e32 v22, v113
	v_mov_b32_e32 v23, v113
	v_mov_b32_e32 v24, v113
	v_mov_b32_e32 v25, v113
	v_mov_b32_e32 v26, v113
	v_mov_b32_e32 v27, v113
	v_mov_b32_e32 v28, v113
	v_mov_b32_e32 v29, v113
	v_add_u32_e32 v163, v3, v2
	v_add_u32_e32 v164, v4, v2
	v_add_u32_e32 v165, v5, v2
	v_add_u32_e32 v166, v6, v2
	v_mov_b64_e32 v[62:63], v[30:31]
	v_mov_b64_e32 v[46:47], v[30:31]
	v_mov_b64_e32 v[0:1], v[16:17]
	v_add_u32_e32 v160, s7, v78
	v_mov_b32_e32 v65, v64
	v_mov_b32_e32 v66, v64
	v_mov_b32_e32 v67, v64
	v_mov_b32_e32 v68, v64
	v_mov_b32_e32 v69, v64
	v_mov_b32_e32 v70, v64
	v_mov_b32_e32 v71, v64
	v_mov_b32_e32 v72, v64
	v_mov_b32_e32 v73, v64
	v_mov_b32_e32 v74, v64
	v_mov_b32_e32 v75, v64
	v_mov_b32_e32 v76, v64
	s_add_i32 s6, s13, 1
	s_add_i32 s72, s11, 0xc0
	v_add_u32_e32 v162, s10, v78
	v_mov_b32_e32 v171, 0xf149f2ca
	v_mov_b32_e32 v156, 0
	v_mov_b32_e32 v77, v64
	v_mov_b32_e32 v78, v64
	v_mov_b32_e32 v79, v64
	v_mov_b64_e32 v[60:61], v[28:29]
	v_mov_b64_e32 v[58:59], v[26:27]
	v_mov_b64_e32 v[56:57], v[24:25]
	v_mov_b64_e32 v[54:55], v[22:23]
	v_mov_b64_e32 v[52:53], v[20:21]
	v_mov_b64_e32 v[50:51], v[18:19]
	v_mov_b64_e32 v[48:49], v[16:17]
	v_mov_b64_e32 v[44:45], v[28:29]
	v_mov_b64_e32 v[42:43], v[26:27]
	v_mov_b64_e32 v[40:41], v[24:25]
	v_mov_b64_e32 v[38:39], v[22:23]
	v_mov_b64_e32 v[36:37], v[20:21]
	v_mov_b64_e32 v[34:35], v[18:19]
	v_mov_b64_e32 v[32:33], v[16:17]
	v_mov_b64_e32 v[2:3], v[18:19]
	v_mov_b64_e32 v[4:5], v[20:21]
	v_mov_b64_e32 v[6:7], v[22:23]
	v_mov_b64_e32 v[8:9], v[24:25]
	v_mov_b64_e32 v[10:11], v[26:27]
	v_mov_b64_e32 v[12:13], v[28:29]
	v_mov_b64_e32 v[14:15], v[30:31]
	s_branch .LBB0_1335

; __device__ __forceinline__ unsigned cvtpk(float lo, float hi) { f32x2_t v = {lo, hi}; bf16x2_t b = __builtin_convertvector(v, bf16x2_t); return __builtin_bit_cast(unsigned, b); }
; #define PV_WAIT(n) do { asm volatile("s_waitcnt lgkmcnt(%0)" :: "i"(n) : "memory"); SBAR(); } while (0)
; template <int VB>
; __device__ __forceinline__ void pv_tile(f32x16* o, int vb0, bf16x8 pa0, bf16x8 pa1, bf16x8 pa2, bf16x8 pa3) {
;     ...
;     s16x4 Al0, Al1, Al2, Al3, Ah0, Ah1, Ah2, Ah3, Bl0, Bl1, Bl2, Bl3, Bh0, Bh1, Bh2, Bh3;
;     PV_RD(A, 0); PV_RD(B, 1); PV_WAIT(8); PV_MM(A, 0);
;     PV_RD(A, 2); PV_WAIT(8); PV_MM(B, 1);
;     PV_RD(B, 3); PV_WAIT(8); PV_MM(A, 2);
;     PV_WAIT(0); PV_MM(B, 3);
;     ...
; }
; __device__ __forceinline__ bf16x8 knorm8(bf16x8 x, const float* g) {
;     const v4u xv = __builtin_bit_cast(v4u, x); float f[8];
; #pragma unroll
;     for (int e = 0; e < 4; ++e) { f[2 * e] = __builtin_bit_cast(float, xv[e] << 16); f[2 * e + 1] = __builtin_bit_cast(float, xv[e] & 0xffff0000u); }
;     float s = 0.f;
; #pragma unroll
;     for (int e = 0; e < 8; ++e) s += f[e] * f[e];
;     s += __shfl_xor(s, 1); s += __shfl_xor(s, 2); s += __shfl_xor(s, 4); s += __shfl_xor(s, 8);
;     const float r = __builtin_amdgcn_rsqf(s * (1.0f / 128.0f) + 1e-6f);
;     const f32x4 g0 = *(const f32x4*)g, g1 = *(const f32x4*)(g + 4);
;     v4u w; w.x = cvtpk(f[0] * r * g0[0], f[1] * r * g0[1]); w.y = cvtpk(f[2] * r * g0[2], f[3] * r * g0[3]); w.z = cvtpk(f[4] * r * g1[0], f[5] * r * g1[1]); w.w = cvtpk(f[6] * r * g1[2], f[7] * r * g1[3]);
;     return __builtin_bit_cast(bf16x8, w);
; __device__ __forceinline__ void fox_attn_unit(const Params& P, char* lds, int b, int h, int qb) {
;     ...
;     float m_reg = -1e30f, l_reg = 0.f; f32x16 o[4] = {};
;     __syncthreads();
;     int j_lo; { const float thr = *(const float*)(ws + WS_THR), cq0 = ckl[q0];
;         const bool skip = lane < 4 * qb && ckl[64 * lane + 63] - cq0 > thr; const unsigned long long bm = __ballot(!skip); j_lo = (int)__builtin_ctzll(bm) & ~1; }
;     SLOAD(NT - 1); SWRITE(0);
;     __syncthreads();
;     for (int t = NT - 1; t > j_lo; t -= 2) {
;         SLOAD(t - 1);
;         { const int kb0 = t * 64; fox_tile<0>(o, m_reg, l_reg, lds, ckl, al_l, vb0, qr, cq, qpos, kb0, kb0 + 63 > qlo, r32, hi); }
;         SWRITE(1);
;         __syncthreads();
.LBB0_1341:
	ds_read_b64_tr_b16 v[120:121], v159 offset:0
	ds_read_b64_tr_b16 v[122:123], v159 offset:0x800
	ds_read_b64_tr_b16 v[124:125], v159 offset:0x1000
	ds_read_b64_tr_b16 v[126:127], v159 offset:0x1800
	ds_read_b64_tr_b16 v[130:131], v159 offset:0x2000
	ds_read_b64_tr_b16 v[132:133], v159 offset:0x2800
	ds_read_b64_tr_b16 v[134:135], v159 offset:0x3000
	ds_read_b64_tr_b16 v[136:137], v159 offset:0x3800
	ds_read_b64_tr_b16 v[178:179], v159 offset:0x200
	ds_read_b64_tr_b16 v[180:181], v159 offset:0xa00
	ds_read_b64_tr_b16 v[182:183], v159 offset:0x1200
	ds_read_b64_tr_b16 v[184:185], v159 offset:0x1a00
	ds_read_b64_tr_b16 v[186:187], v159 offset:0x2200
	ds_read_b64_tr_b16 v[188:189], v159 offset:0x2a00
	ds_read_b64_tr_b16 v[190:191], v159 offset:0x3200
	ds_read_b64_tr_b16 v[192:193], v159 offset:0x3a00
	s_waitcnt lgkmcnt(8)
	s_nop 0
	v_mfma_f32_32x32x16_bf16 v[0:15], v[80:83], v[120:123], v[0:15]
	ds_read_b64_tr_b16 v[120:121], v159 offset:0x400
	ds_read_b64_tr_b16 v[122:123], v159 offset:0xc00
	v_mfma_f32_32x32x16_bf16 v[0:15], v[84:87], v[124:127], v[0:15]
	ds_read_b64_tr_b16 v[124:125], v159 offset:0x1400
	ds_read_b64_tr_b16 v[126:127], v159 offset:0x1c00
	v_mfma_f32_32x32x16_bf16 v[0:15], v[88:91], v[130:133], v[0:15]
	ds_read_b64_tr_b16 v[130:131], v159 offset:0x2400
	ds_read_b64_tr_b16 v[132:133], v159 offset:0x2c00
	v_mfma_f32_32x32x16_bf16 v[0:15], v[92:95], v[134:137], v[0:15]
	ds_read_b64_tr_b16 v[134:135], v159 offset:0x3400
	ds_read_b64_tr_b16 v[136:137], v159 offset:0x3c00
	s_waitcnt lgkmcnt(8)
	v_mfma_f32_32x32x16_bf16 v[32:47], v[80:83], v[178:181], v[32:47]
	ds_read_b64_tr_b16 v[178:179], v159 offset:0x600
	ds_read_b64_tr_b16 v[180:181], v159 offset:0xe00
	v_mfma_f32_32x32x16_bf16 v[32:47], v[84:87], v[182:185], v[32:47]
	ds_read_b64_tr_b16 v[182:183], v159 offset:0x1600
	ds_read_b64_tr_b16 v[184:185], v159 offset:0x1e00
	v_mfma_f32_32x32x16_bf16 v[32:47], v[88:91], v[186:189], v[32:47]
	ds_read_b64_tr_b16 v[186:187], v159 offset:0x2600
	ds_read_b64_tr_b16 v[188:189], v159 offset:0x2e00
	v_mfma_f32_32x32x16_bf16 v[32:47], v[92:95], v[190:193], v[32:47]
	ds_read_b64_tr_b16 v[190:191], v159 offset:0x3600
	ds_read_b64_tr_b16 v[192:193], v159 offset:0x3e00
	s_waitcnt lgkmcnt(8)
	v_mfma_f32_32x32x16_bf16 v[48:63], v[80:83], v[120:123], v[48:63]
	s_waitcnt lgkmcnt(0)
	v_mfma_f32_32x32x16_bf16 v[48:63], v[84:87], v[124:127], v[48:63]
	v_mfma_f32_32x32x16_bf16 v[48:63], v[88:91], v[130:133], v[48:63]
	v_mfma_f32_32x32x16_bf16 v[48:63], v[92:95], v[134:137], v[48:63]
	v_mfma_f32_32x32x16_bf16 v[16:31], v[80:83], v[178:181], v[16:31]
	s_waitcnt vmcnt(3)
	v_lshlrev_b32_e32 v124, 16, v108
	v_and_b32_e32 v125, 0xffff0000, v108
	v_lshlrev_b32_e32 v120, 16, v109
	v_and_b32_e32 v121, 0xffff0000, v109
	v_pk_mul_f32 v[126:127], v[124:125], v[124:125]
	v_pk_mul_f32 v[122:123], v[120:121], v[120:121]
	v_add_f32_e32 v126, v126, v127
	v_mfma_f32_32x32x16_bf16 v[16:31], v[84:87], v[182:185], v[16:31]
	v_add_f32_e32 v122, v122, v126
	v_add_f32_e32 v122, v123, v122
	ds_read_b128 v[80:83], v153
	ds_read_b128 v[84:87], v153 offset:16
	s_cmp_gt_i32 s6, s73
	s_cselect_b64 s[78:79], -1, 0
	s_cmp_le_i32 s6, s73
	s_cselect_b64 s[76:77], -1, 0
	v_mfma_f32_32x32x16_bf16 v[16:31], v[88:91], v[186:189], v[16:31]
	v_lshlrev_b32_e32 v88, 16, v111
	v_and_b32_e32 v89, 0xffff0000, v111
	v_mul_f32_e64 v90, v88, v88
	v_mul_f32_e64 v91, v89, v89
	s_and_b64 vcc, exec, s[76:77]
	v_mfma_f32_32x32x16_bf16 v[16:31], v[92:95], v[190:193], v[16:31]
	v_lshlrev_b32_e32 v92, 16, v110
	v_and_b32_e32 v93, 0xffff0000, v110
	v_mul_f32_e64 v94, v92, v92
	v_mul_f32_e64 v95, v93, v93
	v_add_f32_e32 v94, v94, v122
	v_add_f32_e32 v94, v95, v94
	v_add_f32_e32 v90, v90, v94
	v_add_f32_e32 v90, v91, v90
	s_waitcnt lgkmcnt(0)
	s_nop 0
	v_add_f32_dpp v90, v90, v90 quad_perm:[1,0,3,2] row_mask:0xf bank_mask:0xf
	s_waitcnt lgkmcnt(0)
	s_nop 0
	v_add_f32_dpp v90, v90, v90 quad_perm:[2,3,0,1] row_mask:0xf bank_mask:0xf
	s_waitcnt lgkmcnt(0)
	s_nop 0
	v_add_f32_dpp v90, v90, v90 row_half_mirror row_mask:0xf bank_mask:0xf
	s_waitcnt lgkmcnt(0)
	s_nop 0
	v_add_f32_dpp v90, v90, v90 row_mirror row_mask:0xf bank_mask:0xf
	v_fmamk_f32 v90, v90, 0x3c000000, v141
	v_rsq_f32_e32 v90, v90
	s_nop 0
	v_pk_mul_f32 v[94:95], v[90:91], v[124:125] op_sel_hi:[0,1]
	s_waitcnt vmcnt(2)
	v_lshlrev_b32_e32 v124, 16, v104
	v_and_b32_e32 v125, 0xffff0000, v104
	v_pk_mul_f32 v[80:81], v[80:81], v[94:95]
	v_pk_mul_f32 v[94:95], v[90:91], v[120:121] op_sel_hi:[0,1]
	v_lshlrev_b32_e32 v120, 16, v105
	v_and_b32_e32 v121, 0xffff0000, v105
	v_pk_mul_f32 v[126:127], v[124:125], v[124:125]
	v_pk_mul_f32 v[82:83], v[82:83], v[94:95]
	v_pk_mul_f32 v[122:123], v[120:121], v[120:121]
	v_add_f32_e32 v126, v126, v127
	v_cvt_pk_bf16_f32 v80, v80, v81
	v_cvt_pk_bf16_f32 v81, v82, v83
	v_pk_mul_f32 v[82:83], v[90:91], v[92:93] op_sel_hi:[0,1]
	v_lshlrev_b32_e32 v92, 16, v106
	v_and_b32_e32 v93, 0xffff0000, v106
	v_add_f32_e32 v122, v122, v126
	v_pk_mul_f32 v[94:95], v[92:93], v[92:93]
	v_add_f32_e32 v122, v123, v122
	v_pk_mul_f32 v[82:83], v[84:85], v[82:83]
	v_pk_mul_f32 v[84:85], v[90:91], v[88:89] op_sel_hi:[0,1]
	v_lshlrev_b32_e32 v88, 16, v107
	v_and_b32_e32 v89, 0xffff0000, v107
	v_add_f32_e32 v94, v94, v122
	v_pk_mul_f32 v[90:91], v[88:89], v[88:89]
	v_add_f32_e32 v94, v95, v94
	v_add_f32_e32 v90, v90, v94
	v_add_f32_e32 v90, v91, v90
	v_pk_mul_f32 v[84:85], v[86:87], v[84:85]
	v_cvt_pk_bf16_f32 v82, v82, v83
	v_cvt_pk_bf16_f32 v83, v84, v85
	ds_write_b128 v154, v[80:83] offset:49152
	s_waitcnt lgkmcnt(1)
	v_add_f32_dpp v90, v90, v90 quad_perm:[1,0,3,2] row_mask:0xf bank_mask:0xf
	ds_read_b128 v[80:83], v153
	ds_read_b128 v[84:87], v153 offset:16
	s_waitcnt lgkmcnt(2)
	v_add_f32_dpp v90, v90, v90 quad_perm:[2,3,0,1] row_mask:0xf bank_mask:0xf
	s_waitcnt lgkmcnt(0)
	s_nop 0
	v_add_f32_dpp v90, v90, v90 row_half_mirror row_mask:0xf bank_mask:0xf
	s_waitcnt lgkmcnt(0)
	s_nop 0
	v_add_f32_dpp v90, v90, v90 row_mirror row_mask:0xf bank_mask:0xf
	v_fmamk_f32 v90, v90, 0x3c000000, v141
	v_rsq_f32_e32 v90, v90
	s_nop 0
	v_pk_mul_f32 v[94:95], v[90:91], v[124:125] op_sel_hi:[0,1]
	v_pk_mul_f32 v[80:81], v[80:81], v[94:95]
	v_pk_mul_f32 v[94:95], v[90:91], v[120:121] op_sel_hi:[0,1]
	v_pk_mul_f32 v[82:83], v[82:83], v[94:95]
	v_cvt_pk_bf16_f32 v80, v80, v81
	v_cvt_pk_bf16_f32 v81, v82, v83
	v_pk_mul_f32 v[82:83], v[90:91], v[92:93] op_sel_hi:[0,1]
	v_pk_mul_f32 v[82:83], v[84:85], v[82:83]
	v_pk_mul_f32 v[84:85], v[90:91], v[88:89] op_sel_hi:[0,1]
	v_pk_mul_f32 v[84:85], v[86:87], v[84:85]
	v_cvt_pk_bf16_f32 v82, v82, v83
	v_cvt_pk_bf16_f32 v83, v84, v85
	ds_write_b128 v154, v[80:83] offset:57344
	s_waitcnt vmcnt(1)
	ds_write_b128 v157, v[96:99] offset:16384
	s_waitcnt vmcnt(0)
	ds_write_b128 v158, v[100:103] offset:16384
	s_waitcnt lgkmcnt(0)
	s_barrier
; #define SLOAD(t) do { const size_t r0_ = (size_t)((t) * 64 + sr) * LD1 + sc; st_k0 = *(const bf16x8*)(Kh + r0_); st_k1 = *(const bf16x8*)(Kh + r0_ + (size_t)32 * LD1); \
;         st_v0 = *(const bf16x8*)(Vh + r0_); st_v1 = *(const bf16x8*)(Vh + r0_ + (size_t)32 * LD1); } while (0)
; __device__ __forceinline__ void fox_attn_unit(const Params& P, char* lds, int b, int h, int qb) {
;     ...
;         if (t - 2 > j_lo) SLOAD(t - 2);
	s_cbranch_vccnz .LBB0_1343
	v_lshl_add_u64 v[80:81], v[116:117], 0, v[112:113]
	v_add_co_u32_e32 v82, vcc, 0x11401000, v80
	s_nop 1
	v_addc_co_u32_e32 v83, vcc, 0, v81, vcc
	v_add_co_u32_e32 v84, vcc, 0x11481000, v80
	s_nop 1
	v_addc_co_u32_e32 v85, vcc, 0, v81, vcc
	global_load_dwordx4 v[108:111], v[82:83], off
	global_load_dwordx4 v[104:107], v[84:85], off
	v_add_co_u32_e32 v82, vcc, 0x11402000, v80
	s_nop 1
	v_addc_co_u32_e32 v83, vcc, 0, v81, vcc
	v_add_co_u32_e32 v80, vcc, 0x11482000, v80
	s_nop 1
	v_addc_co_u32_e32 v81, vcc, 0, v81, vcc
	global_load_dwordx4 v[96:99], v[82:83], off
	global_load_dwordx4 v[100:103], v[80:81], off

; __device__ __forceinline__ unsigned cvtpk(float lo, float hi) { f32x2_t v = {lo, hi}; bf16x2_t b = __builtin_convertvector(v, bf16x2_t); return __builtin_bit_cast(unsigned, b); }
; #define PV_RD(S, d0) do { constexpr int b_ = VB * SHM_V + v_rd_off(d0, 0, 0); \
;         TRRD(S##l0, b_); TRRD(S##h0, b_ + 2048); TRRD(S##l1, b_ + 4096); TRRD(S##h1, b_ + 6144); TRRD(S##l2, b_ + 8192); TRRD(S##h2, b_ + 10240); TRRD(S##l3, b_ + 12288); TRRD(S##h3, b_ + 14336); } while (0)
; #define PV_WAIT(n) do { asm volatile("s_waitcnt lgkmcnt(%0)" :: "i"(n) : "memory"); SBAR(); } while (0)
; template <int VB>
; __device__ __forceinline__ void pv_tile(f32x16* o, int vb0, bf16x8 pa0, bf16x8 pa1, bf16x8 pa2, bf16x8 pa3) {
;     ...
;     s16x4 Al0, Al1, Al2, Al3, Ah0, Ah1, Ah2, Ah3, Bl0, Bl1, Bl2, Bl3, Bh0, Bh1, Bh2, Bh3;
;     PV_RD(A, 0); PV_RD(B, 1); PV_WAIT(8); PV_MM(A, 0);
;     PV_RD(A, 2); PV_WAIT(8); PV_MM(B, 1);
;     PV_RD(B, 3); PV_WAIT(8); PV_MM(A, 2);
;     PV_WAIT(0); PV_MM(B, 3);
;     ...
; }
; __device__ __forceinline__ bf16x8 knorm8(bf16x8 x, const float* g) {
;     const v4u xv = __builtin_bit_cast(v4u, x); float f[8];
; #pragma unroll
;     for (int e = 0; e < 4; ++e) { f[2 * e] = __builtin_bit_cast(float, xv[e] << 16); f[2 * e + 1] = __builtin_bit_cast(float, xv[e] & 0xffff0000u); }
;     float s = 0.f;
; #pragma unroll
;     for (int e = 0; e < 8; ++e) s += f[e] * f[e];
;     s += __shfl_xor(s, 1); s += __shfl_xor(s, 2); s += __shfl_xor(s, 4); s += __shfl_xor(s, 8);
;     const float r = __builtin_amdgcn_rsqf(s * (1.0f / 128.0f) + 1e-6f);
;     const f32x4 g0 = *(const f32x4*)g, g1 = *(const f32x4*)(g + 4);
;     v4u w; w.x = cvtpk(f[0] * r * g0[0], f[1] * r * g0[1]); w.y = cvtpk(f[2] * r * g0[2], f[3] * r * g0[3]); w.z = cvtpk(f[4] * r * g1[0], f[5] * r * g1[1]); w.w = cvtpk(f[6] * r * g1[2], f[7] * r * g1[3]);
;     return __builtin_bit_cast(bf16x8, w);
; __device__ __forceinline__ void fox_attn_unit(const Params& P, char* lds, int b, int h, int qb) {
;     ...
;         { const int kb0 = (t - 1) * 64; fox_tile<1>(o, m_reg, l_reg, lds, ckl, al_l, vb0, qr, cq, qpos, kb0, kb0 + 63 > qlo, r32, hi); }
;         if (t - 2 > j_lo) SWRITE(0);
.LBB0_1349:
	ds_read_b64_tr_b16 v[124:125], v159 offset:0x4000
	ds_read_b64_tr_b16 v[126:127], v159 offset:0x4800
	ds_read_b64_tr_b16 v[130:131], v159 offset:0x5000
	ds_read_b64_tr_b16 v[132:133], v159 offset:0x5800
	ds_read_b64_tr_b16 v[134:135], v159 offset:0x6000
	ds_read_b64_tr_b16 v[136:137], v159 offset:0x6800
	ds_read_b64_tr_b16 v[178:179], v159 offset:0x7000
	ds_read_b64_tr_b16 v[180:181], v159 offset:0x7800
	ds_read_b64_tr_b16 v[182:183], v159 offset:0x4200
	ds_read_b64_tr_b16 v[184:185], v159 offset:0x4a00
	ds_read_b64_tr_b16 v[186:187], v159 offset:0x5200
	ds_read_b64_tr_b16 v[188:189], v159 offset:0x5a00
	ds_read_b64_tr_b16 v[190:191], v159 offset:0x6200
	ds_read_b64_tr_b16 v[192:193], v159 offset:0x6a00
	ds_read_b64_tr_b16 v[194:195], v159 offset:0x7200
	ds_read_b64_tr_b16 v[196:197], v159 offset:0x7a00
	s_waitcnt lgkmcnt(8)
	s_nop 0
	v_mfma_f32_32x32x16_bf16 v[0:15], v[80:83], v[124:127], v[0:15]
	ds_read_b64_tr_b16 v[124:125], v159 offset:0x4400
	ds_read_b64_tr_b16 v[126:127], v159 offset:0x4c00
	v_mfma_f32_32x32x16_bf16 v[0:15], v[84:87], v[130:133], v[0:15]
	ds_read_b64_tr_b16 v[130:131], v159 offset:0x5400
	ds_read_b64_tr_b16 v[132:133], v159 offset:0x5c00
	v_mfma_f32_32x32x16_bf16 v[0:15], v[88:91], v[134:137], v[0:15]
	ds_read_b64_tr_b16 v[134:135], v159 offset:0x6400
	ds_read_b64_tr_b16 v[136:137], v159 offset:0x6c00
	v_mfma_f32_32x32x16_bf16 v[0:15], v[92:95], v[178:181], v[0:15]
	ds_read_b64_tr_b16 v[178:179], v159 offset:0x7400
	ds_read_b64_tr_b16 v[180:181], v159 offset:0x7c00
	s_waitcnt lgkmcnt(8)
	v_mfma_f32_32x32x16_bf16 v[32:47], v[80:83], v[182:185], v[32:47]
	ds_read_b64_tr_b16 v[182:183], v159 offset:0x4600
	ds_read_b64_tr_b16 v[184:185], v159 offset:0x4e00
	v_mfma_f32_32x32x16_bf16 v[32:47], v[84:87], v[186:189], v[32:47]
	ds_read_b64_tr_b16 v[186:187], v159 offset:0x5600
	ds_read_b64_tr_b16 v[188:189], v159 offset:0x5e00
	v_mfma_f32_32x32x16_bf16 v[32:47], v[88:91], v[190:193], v[32:47]
	ds_read_b64_tr_b16 v[190:191], v159 offset:0x6600
	ds_read_b64_tr_b16 v[192:193], v159 offset:0x6e00
	v_mfma_f32_32x32x16_bf16 v[32:47], v[92:95], v[194:197], v[32:47]
	ds_read_b64_tr_b16 v[194:195], v159 offset:0x7600
	ds_read_b64_tr_b16 v[196:197], v159 offset:0x7e00
	s_waitcnt lgkmcnt(8)
	v_mfma_f32_32x32x16_bf16 v[48:63], v[80:83], v[124:127], v[48:63]
	s_waitcnt lgkmcnt(0)
	v_mfma_f32_32x32x16_bf16 v[48:63], v[84:87], v[130:133], v[48:63]
	v_mfma_f32_32x32x16_bf16 v[48:63], v[88:91], v[134:137], v[48:63]
	v_mfma_f32_32x32x16_bf16 v[48:63], v[92:95], v[178:181], v[48:63]
	v_mfma_f32_32x32x16_bf16 v[16:31], v[80:83], v[182:185], v[16:31]
	s_andn2_b64 vcc, exec, s[78:79]
	v_mfma_f32_32x32x16_bf16 v[16:31], v[84:87], v[186:189], v[16:31]
	v_mfma_f32_32x32x16_bf16 v[16:31], v[88:91], v[190:193], v[16:31]
	v_mfma_f32_32x32x16_bf16 v[16:31], v[92:95], v[194:197], v[16:31]
	s_cbranch_vccnz .LBB0_1334
	s_waitcnt vmcnt(3)
	v_lshlrev_b32_e32 v94, 16, v108
	v_and_b32_e32 v95, 0xffff0000, v108
	v_lshlrev_b32_e32 v92, 16, v109
	v_and_b32_e32 v93, 0xffff0000, v109
	v_pk_mul_f32 v[86:87], v[94:95], v[94:95]
	v_pk_mul_f32 v[84:85], v[92:93], v[92:93]
	v_add_f32_e32 v86, v86, v87
	v_lshlrev_b32_e32 v90, 16, v110
	v_and_b32_e32 v91, 0xffff0000, v110
	v_add_f32_e32 v84, v84, v86
	v_pk_mul_f32 v[82:83], v[90:91], v[90:91]
	v_add_f32_e32 v84, v85, v84
	v_lshlrev_b32_e32 v88, 16, v111
	v_and_b32_e32 v89, 0xffff0000, v111
	v_add_f32_e32 v82, v82, v84
	v_pk_mul_f32 v[80:81], v[88:89], v[88:89]
	v_add_f32_e32 v82, v83, v82
	v_add_f32_e32 v80, v80, v82
	v_add_f32_e32 v80, v81, v80
	s_waitcnt vmcnt(2)
	v_lshlrev_b32_e32 v126, 16, v104
	v_and_b32_e32 v127, 0xffff0000, v104
	v_lshlrev_b32_e32 v124, 16, v105
	v_and_b32_e32 v125, 0xffff0000, v105
	s_waitcnt lgkmcnt(0)
	v_add_f32_dpp v80, v80, v80 quad_perm:[1,0,3,2] row_mask:0xf bank_mask:0xf
	v_pk_mul_f32 v[86:87], v[126:127], v[126:127]
	v_lshlrev_b32_e32 v110, 16, v106
	v_and_b32_e32 v111, 0xffff0000, v106
	v_add_f32_e32 v86, v86, v87
	s_waitcnt lgkmcnt(0)
	v_add_f32_dpp v80, v80, v80 quad_perm:[2,3,0,1] row_mask:0xf bank_mask:0xf
	v_pk_mul_f32 v[82:83], v[110:111], v[110:111]
	v_lshlrev_b32_e32 v108, 16, v107
	v_and_b32_e32 v109, 0xffff0000, v107
	s_waitcnt lgkmcnt(0)
	v_add_f32_dpp v84, v80, v80 row_half_mirror row_mask:0xf bank_mask:0xf
	v_pk_mul_f32 v[80:81], v[108:109], v[108:109]
	s_waitcnt lgkmcnt(0)
	v_add_f32_dpp v84, v84, v84 row_mirror row_mask:0xf bank_mask:0xf
	v_fmamk_f32 v84, v84, 0x3c000000, v141
	v_rsq_f32_e32 v106, v84
	v_pk_mul_f32 v[84:85], v[124:125], v[124:125]
	v_pk_mul_f32 v[92:93], v[106:107], v[92:93] op_sel_hi:[0,1]
	v_add_f32_e32 v84, v84, v86
	v_add_f32_e32 v84, v85, v84
	v_add_f32_e32 v82, v82, v84
	v_add_f32_e32 v82, v83, v82
	v_add_f32_e32 v80, v80, v82
	v_add_f32_e32 v104, v81, v80
	ds_read_b128 v[80:83], v153
	ds_read_b128 v[84:87], v153 offset:16
	v_pk_mul_f32 v[94:95], v[106:107], v[94:95] op_sel_hi:[0,1]
	s_waitcnt lgkmcnt(2)
	v_add_f32_dpp v104, v104, v104 quad_perm:[1,0,3,2] row_mask:0xf bank_mask:0xf
	s_waitcnt lgkmcnt(1)
	v_pk_mul_f32 v[82:83], v[82:83], v[92:93]
	v_pk_mul_f32 v[80:81], v[80:81], v[94:95]
	s_waitcnt lgkmcnt(0)
	v_add_f32_dpp v92, v104, v104 quad_perm:[2,3,0,1] row_mask:0xf bank_mask:0xf
	v_cvt_pk_bf16_f32 v80, v80, v81
	v_cvt_pk_bf16_f32 v81, v82, v83
	v_pk_mul_f32 v[82:83], v[106:107], v[90:91] op_sel_hi:[0,1]
	v_pk_mul_f32 v[82:83], v[84:85], v[82:83]
	s_waitcnt lgkmcnt(0)
	v_add_f32_dpp v90, v92, v92 row_half_mirror row_mask:0xf bank_mask:0xf
	v_pk_mul_f32 v[84:85], v[106:107], v[88:89] op_sel_hi:[0,1]
	v_pk_mul_f32 v[84:85], v[86:87], v[84:85]
	v_cvt_pk_bf16_f32 v82, v82, v83
	v_cvt_pk_bf16_f32 v83, v84, v85
	ds_write_b128 v154, v[80:83] offset:32768
	s_waitcnt lgkmcnt(1)
	v_add_f32_dpp v80, v90, v90 row_mirror row_mask:0xf bank_mask:0xf
	v_fmamk_f32 v80, v80, 0x3c000000, v141
	v_rsq_f32_e32 v88, v80
	ds_read_b128 v[80:83], v153
	ds_read_b128 v[84:87], v153 offset:16
	v_pk_mul_f32 v[90:91], v[88:89], v[126:127] op_sel_hi:[0,1]
	s_waitcnt lgkmcnt(1)
	v_pk_mul_f32 v[80:81], v[80:81], v[90:91]
	v_pk_mul_f32 v[90:91], v[88:89], v[124:125] op_sel_hi:[0,1]
	v_pk_mul_f32 v[82:83], v[82:83], v[90:91]
	v_cvt_pk_bf16_f32 v80, v80, v81
	v_cvt_pk_bf16_f32 v81, v82, v83
	v_pk_mul_f32 v[82:83], v[88:89], v[110:111] op_sel_hi:[0,1]
	s_waitcnt lgkmcnt(0)
	v_pk_mul_f32 v[82:83], v[84:85], v[82:83]
	v_pk_mul_f32 v[84:85], v[88:89], v[108:109] op_sel_hi:[0,1]
	v_pk_mul_f32 v[84:85], v[86:87], v[84:85]
	v_cvt_pk_bf16_f32 v82, v82, v83
	v_cvt_pk_bf16_f32 v83, v84, v85
	ds_write_b128 v154, v[80:83] offset:40960
	s_waitcnt vmcnt(1)
	ds_write_b128 v157, v[96:99]
	s_waitcnt vmcnt(0)
	ds_write_b128 v158, v[100:103]
	s_branch .LBB0_1334

; __device__ __forceinline__ unsigned cvtpk(float lo, float hi) { f32x2_t v = {lo, hi}; bf16x2_t b = __builtin_convertvector(v, bf16x2_t); return __builtin_bit_cast(unsigned, b); }
; __device__ __forceinline__ int v_st(int k, int c) { const int kk = (k & ~0xC) | ((k & 4) << 1) | ((k & 8) >> 1); return ((kk >> 3) * 4 + (c >> 5)) * 512 + ((kk & 7) * 32 + (c & 31)) * 2; }
; __device__ __forceinline__ int v_rd_base(int lane) { return ((lane & 3) << 3) | (((lane >> 2) & 3) << 6) | (((lane >> 4) & 1) << 5) | (((lane >> 5) & 1) << 8); }
; __device__ __forceinline__ bf16x8 knorm8(bf16x8 x, const float* g) {
;     const v4u xv = __builtin_bit_cast(v4u, x); float f[8];
; #pragma unroll
;     for (int e = 0; e < 4; ++e) { f[2 * e] = __builtin_bit_cast(float, xv[e] << 16); f[2 * e + 1] = __builtin_bit_cast(float, xv[e] & 0xffff0000u); }
;     float s = 0.f;
; #pragma unroll
;     for (int e = 0; e < 8; ++e) s += f[e] * f[e];
;     s += __shfl_xor(s, 1); s += __shfl_xor(s, 2); s += __shfl_xor(s, 4); s += __shfl_xor(s, 8);
;     const float r = __builtin_amdgcn_rsqf(s * (1.0f / 128.0f) + 1e-6f);
;     const f32x4 g0 = *(const f32x4*)g, g1 = *(const f32x4*)(g + 4);
;     v4u w; w.x = cvtpk(f[0] * r * g0[0], f[1] * r * g0[1]); w.y = cvtpk(f[2] * r * g0[2], f[3] * r * g0[3]); w.z = cvtpk(f[4] * r * g1[0], f[5] * r * g1[1]); w.w = cvtpk(f[6] * r * g1[2], f[7] * r * g1[3]);
;     return __builtin_bit_cast(bf16x8, w);
; __device__ __forceinline__ void fox_attn_unit(const Params& P, char* lds, int b, int h, int qb) {
;     ...
;     const int sr = tid >> 4, sc = (tid & 15) * 8, vst0 = v_st(sr, sc), vst1 = v_st(32 + sr, sc), kws = KSWZ(sr, sc * 2);
;     const int vb0 = (int)(uintptr_t)V_lds + v_rd_base(lane);
;     const int NT = 4 * (qb + 1);
;     bf16x8 st_k0, st_k1, st_v0, st_v1;
;     for (int i = tid; i < (q0 + 256) / 4; i += NTHREADS) ((f32x4*)ckl)[i] = ((const f32x4*)CF)[i];
;     ...
;     float m_reg = -1e30f, l_reg = 0.f; f32x16 o[4] = {};
;     __syncthreads();
;     int j_lo; { const float thr = *(const float*)(ws + WS_THR), cq0 = ckl[q0];
;         const bool skip = lane < 4 * qb && ckl[64 * lane + 63] - cq0 > thr; const unsigned long long bm = __ballot(!skip); j_lo = (int)__builtin_ctzll(bm) & ~1; }
;     SLOAD(NT - 1); SWRITE(0);
;     __syncthreads();
;     for (int t = NT - 1; t > j_lo; t -= 2) {
.LBB0_1363:
	s_or_b64 exec, exec, s[8:9]
	v_ashrrev_i32_e32 v77, 4, v114
	s_or_b32 s8, s11, 3
	v_lshlrev_b32_e32 v8, 3, v114
	v_lshl_add_u32 v0, s8, 6, v77
	v_and_b32_e32 v9, 0x78, v8
	v_ashrrev_i32_e32 v1, 31, v0
	v_lshlrev_b32_e32 v10, 1, v9
	v_lshlrev_b64 v[16:17], 14, v[0:1]
	v_or_b32_e32 v16, v16, v10
	v_lshl_add_u64 v[4:5], s[74:75], 0, v[16:17]
	global_load_dwordx4 v[0:3], v[4:5], off
	s_mov_b32 s9, 0x80000
	v_add_co_u32_e32 v4, vcc, s9, v4
	s_and_b32 s7, s7, 0x3fffffc0
	s_nop 0
	v_addc_co_u32_e32 v5, vcc, 0, v5, vcc
	global_load_dwordx4 v[4:7], v[4:5], off
	v_cndmask_b32_e64 v12, 0, 1, s[0:1]
	v_and_b32_e32 v13, 0xfffff0, v77
	v_lshlrev_b32_e32 v14, 1, v77
	v_lshrrev_b32_e32 v15, 1, v77
	v_bfe_u32 v46, v8, 5, 2
	v_and_b32_e32 v8, 3, v77
	v_add_u32_e32 v18, 32, v77
	s_lshl_b32 s0, s7, 2
	v_lshl_add_u64 v[16:17], s[84:85], 0, v[16:17]
	v_and_b32_e32 v11, 0x70, v114
	v_lshlrev_b32_e32 v19, 8, v77
	v_cmp_ne_u32_e32 vcc, 0, v12
	v_and_or_b32 v12, v14, 8, v13
	v_and_or_b32 v8, v15, 4, v8
	v_and_b32_e32 v13, 0xfffff0, v18
	v_lshlrev_b32_e32 v14, 1, v18
	s_add_i32 s41, s0, 0
	v_lshl_add_u32 v9, v9, 2, 0
	v_add_co_u32_e64 v20, s[0:1], s9, v16
	v_lshrrev_b32_e32 v12, 1, v12
	v_lshlrev_b32_e32 v47, 6, v8
	v_and_or_b32 v8, v14, 8, v13
	v_bitop3_b32 v18, v10, v19, v11 bitop3:0xde
	v_add_u32_e32 v153, 0x24800, v9
	v_addc_co_u32_e64 v21, s[0:1], 0, v17, s[0:1]
	v_and_b32_e32 v48, 48, v10
	v_or_b32_e32 v49, v12, v46
	v_lshrrev_b32_e32 v50, 1, v8
	ds_read_b128 v[8:11], v153
	ds_read_b128 v[12:15], v153 offset:16
	v_add_u32_e32 v154, 0, v18
	global_load_dwordx4 v[16:19], v[16:17], off
	s_nop 0
	global_load_dwordx4 v[20:23], v[20:21], off
	v_readlane_b32 s10, v236, 30
	s_and_b32 s10, s10, 7
	s_ff1_i32_b64 s0, vcc
	s_lshl_b32 s7, s10, 8
	s_add_i32 s41, s41, 0x14000
	s_and_b32 s77, s0, 62
	s_cmp_le_u32 s8, s77
	v_lshlrev_b32_e32 v115, 4, v151
	v_cmp_gt_u32_e64 s[8:9], 32, v151
	v_lshl_add_u32 v152, v150, 2, s41
	v_mov_b32_e32 v63, 0
	v_mov_b32_e32 v62, 0
	v_mov_b32_e32 v61, 0
	v_mov_b32_e32 v60, 0
	v_mov_b32_e32 v59, 0
	v_mov_b32_e32 v58, 0
	v_mov_b32_e32 v57, 0
	v_mov_b32_e32 v56, 0
	v_mov_b32_e32 v55, 0
	v_mov_b32_e32 v54, 0
	v_mov_b32_e32 v53, 0
	v_mov_b32_e32 v52, 0
	v_mov_b32_e32 v155, 0
	s_waitcnt vmcnt(3)
	v_lshlrev_b32_e32 v28, 16, v0
	v_and_b32_e32 v29, 0xffff0000, v0
	v_lshlrev_b32_e32 v24, 16, v3
	v_and_b32_e32 v25, 0xffff0000, v3
	v_lshlrev_b32_e32 v26, 16, v2
	v_and_b32_e32 v27, 0xffff0000, v2
	v_lshlrev_b32_e32 v2, 16, v1
	v_and_b32_e32 v3, 0xffff0000, v1
	v_pk_mul_f32 v[34:35], v[28:29], v[28:29]
	v_pk_mul_f32 v[32:33], v[2:3], v[2:3]
	v_add_f32_e32 v51, v34, v35
	v_add_f32_e32 v32, v32, v51
	v_pk_mul_f32 v[30:31], v[26:27], v[26:27]
	v_add_f32_e32 v32, v33, v32
	v_add_f32_e32 v30, v30, v32
	v_pk_mul_f32 v[0:1], v[24:25], v[24:25]
	v_add_f32_e32 v30, v31, v30
	v_add_f32_e32 v0, v0, v30
	s_waitcnt vmcnt(2)
	v_lshlrev_b32_e32 v42, 16, v4
	v_and_b32_e32 v43, 0xffff0000, v4
	v_add_f32_e32 v0, v1, v0
	v_lshlrev_b32_e32 v40, 16, v5
	v_and_b32_e32 v41, 0xffff0000, v5
	v_pk_mul_f32 v[44:45], v[42:43], v[42:43]
	v_pk_mul_f32 v[34:35], v[40:41], v[40:41]
	v_add_f32_e32 v30, v44, v45
	v_lshlrev_b32_e32 v38, 16, v6
	v_and_b32_e32 v39, 0xffff0000, v6
	v_add_f32_e32 v30, v34, v30
	v_lshlrev_b32_e32 v36, 16, v7
	v_and_b32_e32 v37, 0xffff0000, v7
	v_pk_mul_f32 v[6:7], v[38:39], v[38:39]
	v_add_f32_e32 v30, v35, v30
	v_add_f32_e32 v6, v6, v30
	v_pk_mul_f32 v[4:5], v[36:37], v[36:37]
	s_waitcnt lgkmcnt(0)
	v_add_f32_dpp v0, v0, v0 quad_perm:[1,0,3,2] row_mask:0xf bank_mask:0xf
	v_add_f32_e32 v6, v7, v6
	v_add_f32_e32 v4, v4, v6
	v_add_f32_e32 v4, v5, v4
	v_lshlrev_b32_e32 v6, 9, v49
	s_waitcnt lgkmcnt(0)
	v_add_f32_dpp v0, v0, v0 quad_perm:[2,3,0,1] row_mask:0xf bank_mask:0xf
	v_or_b32_e32 v7, v50, v46
	s_waitcnt lgkmcnt(0)
	v_add_f32_dpp v4, v4, v4 quad_perm:[1,0,3,2] row_mask:0xf bank_mask:0xf
	v_or3_b32 v30, v6, v47, v48
	s_waitcnt lgkmcnt(0)
	v_add_f32_dpp v0, v0, v0 row_half_mirror row_mask:0xf bank_mask:0xf
	v_lshlrev_b32_e32 v6, 9, v7
	s_waitcnt lgkmcnt(0)
	v_add_f32_dpp v4, v4, v4 quad_perm:[2,3,0,1] row_mask:0xf bank_mask:0xf
	v_or3_b32 v31, v6, v47, v48
	s_waitcnt lgkmcnt(0)
	v_add_f32_dpp v0, v0, v0 row_mirror row_mask:0xf bank_mask:0xf
	v_fmamk_f32 v0, v0, 0x3c000000, v141
	v_rsq_f32_e32 v0, v0
	s_waitcnt lgkmcnt(0)
	v_add_f32_dpp v32, v4, v4 row_half_mirror row_mask:0xf bank_mask:0xf
	v_add_u32_e32 v156, 0, v30
	v_pk_mul_f32 v[4:5], v[0:1], v[28:29] op_sel_hi:[0,1]
	v_pk_mul_f32 v[2:3], v[0:1], v[2:3] op_sel_hi:[0,1]
	v_pk_mul_f32 v[6:7], v[0:1], v[26:27] op_sel_hi:[0,1]
	v_pk_mul_f32 v[0:1], v[0:1], v[24:25] op_sel_hi:[0,1]
	v_pk_mul_f32 v[4:5], v[8:9], v[4:5]
	v_pk_mul_f32 v[2:3], v[10:11], v[2:3]
	v_pk_mul_f32 v[6:7], v[12:13], v[6:7]
	v_pk_mul_f32 v[8:9], v[14:15], v[0:1]
	v_cvt_pk_bf16_f32 v0, v4, v5
	v_cvt_pk_bf16_f32 v1, v2, v3
	v_cvt_pk_bf16_f32 v2, v6, v7
	v_cvt_pk_bf16_f32 v3, v8, v9
	s_waitcnt lgkmcnt(0)
	v_add_f32_dpp v4, v32, v32 row_mirror row_mask:0xf bank_mask:0xf
	ds_write_b128 v154, v[0:3] offset:32768
	v_fmamk_f32 v4, v4, 0x3c000000, v141
	ds_read_b128 v[0:3], v153
	v_rsq_f32_e32 v8, v4
	ds_read_b128 v[4:7], v153 offset:16
	v_add_u32_e32 v157, 0, v31
	v_mov_b32_e32 v15, 0
	v_pk_mul_f32 v[10:11], v[8:9], v[42:43] op_sel_hi:[0,1]
	s_waitcnt lgkmcnt(1)
	v_pk_mul_f32 v[0:1], v[0:1], v[10:11]
	v_pk_mul_f32 v[10:11], v[8:9], v[40:41] op_sel_hi:[0,1]
	v_pk_mul_f32 v[2:3], v[2:3], v[10:11]
	v_cvt_pk_bf16_f32 v0, v0, v1
	v_cvt_pk_bf16_f32 v1, v2, v3
	v_pk_mul_f32 v[2:3], v[8:9], v[38:39] op_sel_hi:[0,1]
	s_waitcnt lgkmcnt(0)
	v_pk_mul_f32 v[2:3], v[4:5], v[2:3]
	v_pk_mul_f32 v[4:5], v[8:9], v[36:37] op_sel_hi:[0,1]
	v_pk_mul_f32 v[4:5], v[6:7], v[4:5]
	v_cvt_pk_bf16_f32 v2, v2, v3
	v_cvt_pk_bf16_f32 v3, v4, v5
	ds_write_b128 v154, v[0:3] offset:40960
	s_waitcnt vmcnt(1)
	ds_write_b128 v156, v[16:19]
	s_waitcnt vmcnt(0)
	ds_write_b128 v157, v[20:23]
	v_mov_b32_e32 v14, 0
	v_mov_b32_e32 v13, 0
	v_mov_b32_e32 v12, 0
	v_mov_b32_e32 v11, 0
	v_mov_b32_e32 v10, 0
	v_mov_b32_e32 v9, 0
	v_mov_b32_e32 v8, 0
	v_mov_b32_e32 v7, 0
	v_mov_b32_e32 v6, 0
	v_mov_b32_e32 v5, 0
	v_mov_b32_e32 v4, 0
	v_mov_b32_e32 v3, 0
	v_mov_b32_e32 v2, 0
	v_mov_b32_e32 v1, 0
	v_mov_b32_e32 v0, 0
	v_mov_b32_e32 v47, 0
	v_mov_b32_e32 v46, 0
	v_mov_b32_e32 v45, 0
	v_mov_b32_e32 v44, 0
	v_mov_b32_e32 v43, 0
	v_mov_b32_e32 v42, 0
	v_mov_b32_e32 v41, 0
	v_mov_b32_e32 v40, 0
	v_mov_b32_e32 v39, 0
	v_mov_b32_e32 v38, 0
	v_mov_b32_e32 v37, 0
	v_mov_b32_e32 v36, 0
	v_mov_b32_e32 v35, 0
	v_mov_b32_e32 v34, 0
	v_mov_b32_e32 v33, 0
	v_mov_b32_e32 v32, 0
	v_mov_b32_e32 v51, 0
	v_mov_b32_e32 v50, 0
	v_mov_b32_e32 v49, 0
	v_mov_b32_e32 v48, 0
	v_mov_b32_e32 v31, 0
	v_mov_b32_e32 v30, 0
	v_mov_b32_e32 v29, 0
	v_mov_b32_e32 v28, 0
	v_mov_b32_e32 v27, 0
	v_mov_b32_e32 v26, 0
	v_mov_b32_e32 v25, 0
	v_mov_b32_e32 v24, 0
	v_mov_b32_e32 v23, 0
	v_mov_b32_e32 v22, 0
	v_mov_b32_e32 v21, 0
	v_mov_b32_e32 v20, 0
	v_mov_b32_e32 v19, 0
	v_mov_b32_e32 v18, 0
	v_mov_b32_e32 v17, 0
	v_mov_b32_e32 v16, 0
	s_waitcnt lgkmcnt(0)
	s_barrier
; __device__ __forceinline__ int v_rd_base(int lane) { return ((lane & 3) << 3) | (((lane >> 2) & 3) << 6) | (((lane >> 4) & 1) << 5) | (((lane >> 5) & 1) << 8); }
; #define SLOAD(t) do { const size_t r0_ = (size_t)((t) * 64 + sr) * LD1 + sc; st_k0 = *(const bf16x8*)(Kh + r0_); st_k1 = *(const bf16x8*)(Kh + r0_ + (size_t)32 * LD1); \
;         st_v0 = *(const bf16x8*)(Vh + r0_); st_v1 = *(const bf16x8*)(Vh + r0_ + (size_t)32 * LD1); } while (0)
; #define SWRITE(bf) do { *(bf16x8*)(K_lds + (bf) * SHM_K + kws) = knorm8(st_k0, kgl + sc); *(bf16x8*)(K_lds + (bf) * SHM_K + kws + 32 * 256) = knorm8(st_k1, kgl + sc); \
;         *(bf16x8*)(V_lds + (bf) * SHM_V + vst0) = st_v0; *(bf16x8*)(V_lds + (bf) * SHM_V + vst1) = st_v1; } while (0)
; __device__ __forceinline__ void fox_attn_unit(const Params& P, char* lds, int b, int h, int qb) {
;     ...
;     const int vb0 = (int)(uintptr_t)V_lds + v_rd_base(lane);
;     const int NT = 4 * (qb + 1);
;     bf16x8 st_k0, st_k1, st_v0, st_v1;
;     for (int i = tid; i < (q0 + 256) / 4; i += NTHREADS) ((f32x4*)ckl)[i] = ((const f32x4*)CF)[i];
;     ...
;     float m_reg = -1e30f, l_reg = 0.f; f32x16 o[4] = {};
;     __syncthreads();
;     int j_lo; { const float thr = *(const float*)(ws + WS_THR), cq0 = ckl[q0];
;         const bool skip = lane < 4 * qb && ckl[64 * lane + 63] - cq0 > thr; const unsigned long long bm = __ballot(!skip); j_lo = (int)__builtin_ctzll(bm) & ~1; }
;     SLOAD(NT - 1); SWRITE(0);
;     __syncthreads();
;     for (int t = NT - 1; t > j_lo; t -= 2) {
	s_cbranch_scc1 .LBB0_1382
	v_lshlrev_b32_e32 v0, 3, v151
	v_and_b32_e32 v1, 0xc0, v115
	v_lshlrev_b32_e32 v2, 1, v151
	v_and_or_b32 v1, v0, 24, v1
	v_and_b32_e32 v2, 32, v2
	v_and_b32_e32 v0, 0x100, v0
	s_cmp_lg_u32 0, -1
	v_or3_b32 v0, v1, v2, v0
	s_cselect_b32 s0, 0, 0
	v_add_u32_e32 v158, s0, v0
	v_lshlrev_b32_e32 v0, 4, v150
	v_and_b32_e32 v0, 0x70, v0
	v_or_b32_e32 v1, 32, v78
	s_lshl_b32 s0, s10, 2
	v_xad_u32 v4, v1, v0, 0
	v_or_b32_e32 v1, 64, v78
	s_or_b32 s78, s0, 1
	s_add_i32 s79, s7, 0xc0
	s_lshl_b32 s10, s10, 10
	v_xad_u32 v5, v1, v0, 0
	v_or_b32_e32 v1, 0x60, v78
	s_or_b32 s82, s73, 1
	v_readlane_b32 s0, v236, 36
	v_xad_u32 v3, v78, v0, 0
	v_xad_u32 v6, v1, v0, 0
	v_and_b32_e32 v0, 15, v114
	v_add_u32_e32 v8, s7, v77
	s_add_u32 s0, s90, s0
	v_lshlrev_b32_e32 v112, 4, v0
	v_add_u32_e32 v0, 64, v8
	s_addc_u32 s1, s91, 0
	v_ashrrev_i32_e32 v1, 31, v0
	s_add_u32 s0, s0, s2
	v_lshlrev_b64 v[0:1], 14, v[0:1]
	s_addc_u32 s1, s1, s3
	s_add_i32 s2, s40, 0xffffff40
	v_lshlrev_b32_e32 v7, 2, v149
	v_lshl_add_u64 v[116:117], s[0:1], 0, v[0:1]
	v_add_u32_e32 v0, s2, v150
	v_sub_u32_e32 v160, v0, v7
	v_add_u32_e32 v0, 0x80, v8
	v_ashrrev_i32_e32 v1, 31, v0
	v_lshlrev_b32_e32 v2, 8, v150
	s_add_i32 s2, s10, 0
	v_lshlrev_b64 v[0:1], 14, v[0:1]
	v_mov_b32_e32 v16, v113
	v_mov_b32_e32 v17, v113
	v_mov_b32_e32 v30, v113
	v_mov_b32_e32 v31, v113
	s_add_i32 s2, s2, 0x10200
	v_lshl_add_u64 v[118:119], s[0:1], 0, v[0:1]
	v_mov_b32_e32 v18, v113
	v_mov_b32_e32 v19, v113
	v_mov_b32_e32 v20, v113
	v_mov_b32_e32 v21, v113
	v_mov_b32_e32 v22, v113
	v_mov_b32_e32 v23, v113
	v_mov_b32_e32 v24, v113
	v_mov_b32_e32 v25, v113
	v_mov_b32_e32 v26, v113
	v_mov_b32_e32 v27, v113
	v_mov_b32_e32 v28, v113
	v_mov_b32_e32 v29, v113
	v_add_u32_e32 v162, v3, v2
	v_add_u32_e32 v163, v4, v2
	v_add_u32_e32 v164, v5, v2
	v_add_u32_e32 v165, v6, v2
	v_mov_b64_e32 v[62:63], v[30:31]
	v_mov_b64_e32 v[46:47], v[30:31]
	v_mov_b64_e32 v[0:1], v[16:17]
	v_add_u32_e32 v159, s41, v78
	v_mov_b32_e32 v65, v64
	v_mov_b32_e32 v66, v64
	v_mov_b32_e32 v67, v64
	v_mov_b32_e32 v68, v64
	v_mov_b32_e32 v69, v64
	v_mov_b32_e32 v70, v64
	v_mov_b32_e32 v71, v64
	v_mov_b32_e32 v72, v64
	v_mov_b32_e32 v73, v64
	v_mov_b32_e32 v74, v64
	v_mov_b32_e32 v75, v64
	v_mov_b32_e32 v76, v64
	v_add_u32_e32 v161, s2, v78
	v_mov_b32_e32 v170, 0xf149f2ca
	v_mov_b32_e32 v155, 0
	v_mov_b32_e32 v77, v64
	v_mov_b32_e32 v78, v64
	v_mov_b32_e32 v79, v64
	v_mov_b64_e32 v[60:61], v[28:29]
	v_mov_b64_e32 v[58:59], v[26:27]
	v_mov_b64_e32 v[56:57], v[24:25]
	v_mov_b64_e32 v[54:55], v[22:23]
	v_mov_b64_e32 v[52:53], v[20:21]
	v_mov_b64_e32 v[50:51], v[18:19]
	v_mov_b64_e32 v[48:49], v[16:17]
	v_mov_b64_e32 v[44:45], v[28:29]
	v_mov_b64_e32 v[42:43], v[26:27]
	v_mov_b64_e32 v[40:41], v[24:25]
	v_mov_b64_e32 v[38:39], v[22:23]
	v_mov_b64_e32 v[36:37], v[20:21]
	v_mov_b64_e32 v[34:35], v[18:19]
	v_mov_b64_e32 v[32:33], v[16:17]
	v_mov_b64_e32 v[2:3], v[18:19]
	v_mov_b64_e32 v[4:5], v[20:21]
	v_mov_b64_e32 v[6:7], v[22:23]
	v_mov_b64_e32 v[8:9], v[24:25]
	v_mov_b64_e32 v[10:11], v[26:27]
	v_mov_b64_e32 v[12:13], v[28:29]
	v_mov_b64_e32 v[14:15], v[30:31]
	s_branch .LBB0_1366

; __device__ __forceinline__ unsigned cvtpk(float lo, float hi) { f32x2_t v = {lo, hi}; bf16x2_t b = __builtin_convertvector(v, bf16x2_t); return __builtin_bit_cast(unsigned, b); }
; #define PV_RD(S, d0) do { constexpr int b_ = VB * SHM_V + v_rd_off(d0, 0, 0); \
;         TRRD(S##l0, b_); TRRD(S##h0, b_ + 2048); TRRD(S##l1, b_ + 4096); TRRD(S##h1, b_ + 6144); TRRD(S##l2, b_ + 8192); TRRD(S##h2, b_ + 10240); TRRD(S##l3, b_ + 12288); TRRD(S##h3, b_ + 14336); } while (0)
; #define PV_WAIT(n) do { asm volatile("s_waitcnt lgkmcnt(%0)" :: "i"(n) : "memory"); SBAR(); } while (0)
; template <int VB>
; __device__ __forceinline__ void pv_tile(f32x16* o, int vb0, bf16x8 pa0, bf16x8 pa1, bf16x8 pa2, bf16x8 pa3) {
;     ...
;     s16x4 Al0, Al1, Al2, Al3, Ah0, Ah1, Ah2, Ah3, Bl0, Bl1, Bl2, Bl3, Bh0, Bh1, Bh2, Bh3;
;     PV_RD(A, 0); PV_RD(B, 1); PV_WAIT(8); PV_MM(A, 0);
;     PV_RD(A, 2); PV_WAIT(8); PV_MM(B, 1);
;     PV_RD(B, 3); PV_WAIT(8); PV_MM(A, 2);
;     PV_WAIT(0); PV_MM(B, 3);
;     ...
; }
; __device__ __forceinline__ bf16x8 knorm8(bf16x8 x, const float* g) {
;     const v4u xv = __builtin_bit_cast(v4u, x); float f[8];
; #pragma unroll
;     for (int e = 0; e < 4; ++e) { f[2 * e] = __builtin_bit_cast(float, xv[e] << 16); f[2 * e + 1] = __builtin_bit_cast(float, xv[e] & 0xffff0000u); }
;     float s = 0.f;
; #pragma unroll
;     for (int e = 0; e < 8; ++e) s += f[e] * f[e];
;     s += __shfl_xor(s, 1); s += __shfl_xor(s, 2); s += __shfl_xor(s, 4); s += __shfl_xor(s, 8);
;     const float r = __builtin_amdgcn_rsqf(s * (1.0f / 128.0f) + 1e-6f);
;     const f32x4 g0 = *(const f32x4*)g, g1 = *(const f32x4*)(g + 4);
;     v4u w; w.x = cvtpk(f[0] * r * g0[0], f[1] * r * g0[1]); w.y = cvtpk(f[2] * r * g0[2], f[3] * r * g0[3]); w.z = cvtpk(f[4] * r * g1[0], f[5] * r * g1[1]); w.w = cvtpk(f[6] * r * g1[2], f[7] * r * g1[3]);
;     return __builtin_bit_cast(bf16x8, w);
.LBB0_1372:
	ds_read_b64_tr_b16 v[120:121], v158 offset:0
	ds_read_b64_tr_b16 v[122:123], v158 offset:0x800
	ds_read_b64_tr_b16 v[124:125], v158 offset:0x1000
	ds_read_b64_tr_b16 v[126:127], v158 offset:0x1800
	ds_read_b64_tr_b16 v[130:131], v158 offset:0x2000
	ds_read_b64_tr_b16 v[132:133], v158 offset:0x2800
	ds_read_b64_tr_b16 v[134:135], v158 offset:0x3000
	ds_read_b64_tr_b16 v[136:137], v158 offset:0x3800
	ds_read_b64_tr_b16 v[178:179], v158 offset:0x200
	ds_read_b64_tr_b16 v[180:181], v158 offset:0xa00
	ds_read_b64_tr_b16 v[182:183], v158 offset:0x1200
	ds_read_b64_tr_b16 v[184:185], v158 offset:0x1a00
	ds_read_b64_tr_b16 v[186:187], v158 offset:0x2200
	ds_read_b64_tr_b16 v[188:189], v158 offset:0x2a00
	ds_read_b64_tr_b16 v[190:191], v158 offset:0x3200
	ds_read_b64_tr_b16 v[192:193], v158 offset:0x3a00
	s_waitcnt lgkmcnt(8)
	s_nop 0
	v_mfma_f32_32x32x16_bf16 v[0:15], v[80:83], v[120:123], v[0:15]
	ds_read_b64_tr_b16 v[120:121], v158 offset:0x400
	ds_read_b64_tr_b16 v[122:123], v158 offset:0xc00
	v_mfma_f32_32x32x16_bf16 v[0:15], v[84:87], v[124:127], v[0:15]
	ds_read_b64_tr_b16 v[124:125], v158 offset:0x1400
	ds_read_b64_tr_b16 v[126:127], v158 offset:0x1c00
	v_mfma_f32_32x32x16_bf16 v[0:15], v[88:91], v[130:133], v[0:15]
	ds_read_b64_tr_b16 v[130:131], v158 offset:0x2400
	ds_read_b64_tr_b16 v[132:133], v158 offset:0x2c00
	v_mfma_f32_32x32x16_bf16 v[0:15], v[92:95], v[134:137], v[0:15]
	ds_read_b64_tr_b16 v[134:135], v158 offset:0x3400
	ds_read_b64_tr_b16 v[136:137], v158 offset:0x3c00
	s_waitcnt lgkmcnt(8)
	v_mfma_f32_32x32x16_bf16 v[32:47], v[80:83], v[178:181], v[32:47]
	ds_read_b64_tr_b16 v[178:179], v158 offset:0x600
	ds_read_b64_tr_b16 v[180:181], v158 offset:0xe00
	v_mfma_f32_32x32x16_bf16 v[32:47], v[84:87], v[182:185], v[32:47]
	ds_read_b64_tr_b16 v[182:183], v158 offset:0x1600
	ds_read_b64_tr_b16 v[184:185], v158 offset:0x1e00
	v_mfma_f32_32x32x16_bf16 v[32:47], v[88:91], v[186:189], v[32:47]
	ds_read_b64_tr_b16 v[186:187], v158 offset:0x2600
	ds_read_b64_tr_b16 v[188:189], v158 offset:0x2e00
	v_mfma_f32_32x32x16_bf16 v[32:47], v[92:95], v[190:193], v[32:47]
	ds_read_b64_tr_b16 v[190:191], v158 offset:0x3600
	ds_read_b64_tr_b16 v[192:193], v158 offset:0x3e00
	s_waitcnt lgkmcnt(8)
	v_mfma_f32_32x32x16_bf16 v[48:63], v[80:83], v[120:123], v[48:63]
	s_waitcnt lgkmcnt(0)
	v_mfma_f32_32x32x16_bf16 v[48:63], v[84:87], v[124:127], v[48:63]
	v_mfma_f32_32x32x16_bf16 v[48:63], v[88:91], v[130:133], v[48:63]
	v_mfma_f32_32x32x16_bf16 v[48:63], v[92:95], v[134:137], v[48:63]
	v_mfma_f32_32x32x16_bf16 v[16:31], v[80:83], v[178:181], v[16:31]
	s_waitcnt vmcnt(3)
	v_lshlrev_b32_e32 v124, 16, v108
	v_and_b32_e32 v125, 0xffff0000, v108
	v_lshlrev_b32_e32 v120, 16, v109
	v_and_b32_e32 v121, 0xffff0000, v109
	v_pk_mul_f32 v[126:127], v[124:125], v[124:125]
	v_pk_mul_f32 v[122:123], v[120:121], v[120:121]
	v_add_f32_e32 v126, v126, v127
	v_mfma_f32_32x32x16_bf16 v[16:31], v[84:87], v[182:185], v[16:31]
	v_add_f32_e32 v122, v122, v126
	v_add_f32_e32 v122, v123, v122
	ds_read_b128 v[80:83], v153
	ds_read_b128 v[84:87], v153 offset:16
	s_cmp_gt_i32 s78, s77
	s_cselect_b64 s[74:75], -1, 0
	s_cmp_le_i32 s78, s77
	s_cselect_b64 s[2:3], -1, 0
	v_mfma_f32_32x32x16_bf16 v[16:31], v[88:91], v[186:189], v[16:31]
	v_lshlrev_b32_e32 v88, 16, v111
	v_and_b32_e32 v89, 0xffff0000, v111
	v_mul_f32_e64 v90, v88, v88
	v_mul_f32_e64 v91, v89, v89
	s_and_b64 vcc, exec, s[2:3]
	v_mfma_f32_32x32x16_bf16 v[16:31], v[92:95], v[190:193], v[16:31]
	v_lshlrev_b32_e32 v92, 16, v110
	v_and_b32_e32 v93, 0xffff0000, v110
	v_mul_f32_e64 v94, v92, v92
	v_mul_f32_e64 v95, v93, v93
	v_add_f32_e32 v94, v94, v122
	v_add_f32_e32 v94, v95, v94
	v_add_f32_e32 v90, v90, v94
	v_add_f32_e32 v90, v91, v90
	s_waitcnt lgkmcnt(0)
	s_nop 0
	v_add_f32_dpp v90, v90, v90 quad_perm:[1,0,3,2] row_mask:0xf bank_mask:0xf
	s_waitcnt lgkmcnt(0)
	s_nop 0
	v_add_f32_dpp v90, v90, v90 quad_perm:[2,3,0,1] row_mask:0xf bank_mask:0xf
	s_waitcnt lgkmcnt(0)
	s_nop 0
	v_add_f32_dpp v90, v90, v90 row_half_mirror row_mask:0xf bank_mask:0xf
	s_waitcnt lgkmcnt(0)
	s_nop 0
	v_add_f32_dpp v90, v90, v90 row_mirror row_mask:0xf bank_mask:0xf
	v_fmamk_f32 v90, v90, 0x3c000000, v141
	v_rsq_f32_e32 v90, v90
	s_nop 0
	v_pk_mul_f32 v[94:95], v[90:91], v[124:125] op_sel_hi:[0,1]
	s_waitcnt vmcnt(2)
	v_lshlrev_b32_e32 v124, 16, v104
	v_and_b32_e32 v125, 0xffff0000, v104
	v_pk_mul_f32 v[80:81], v[80:81], v[94:95]
	v_pk_mul_f32 v[94:95], v[90:91], v[120:121] op_sel_hi:[0,1]
	v_lshlrev_b32_e32 v120, 16, v105
	v_and_b32_e32 v121, 0xffff0000, v105
	v_pk_mul_f32 v[126:127], v[124:125], v[124:125]
	v_pk_mul_f32 v[82:83], v[82:83], v[94:95]
	v_pk_mul_f32 v[122:123], v[120:121], v[120:121]
	v_add_f32_e32 v126, v126, v127
	v_cvt_pk_bf16_f32 v80, v80, v81
	v_cvt_pk_bf16_f32 v81, v82, v83
	v_pk_mul_f32 v[82:83], v[90:91], v[92:93] op_sel_hi:[0,1]
	v_lshlrev_b32_e32 v92, 16, v106
	v_and_b32_e32 v93, 0xffff0000, v106
	v_add_f32_e32 v122, v122, v126
	v_pk_mul_f32 v[94:95], v[92:93], v[92:93]
	v_add_f32_e32 v122, v123, v122
	v_pk_mul_f32 v[82:83], v[84:85], v[82:83]
	v_pk_mul_f32 v[84:85], v[90:91], v[88:89] op_sel_hi:[0,1]
	v_lshlrev_b32_e32 v88, 16, v107
	v_and_b32_e32 v89, 0xffff0000, v107
	v_add_f32_e32 v94, v94, v122
	v_pk_mul_f32 v[90:91], v[88:89], v[88:89]
	v_add_f32_e32 v94, v95, v94
	v_add_f32_e32 v90, v90, v94
	v_add_f32_e32 v90, v91, v90
	v_pk_mul_f32 v[84:85], v[86:87], v[84:85]
	v_cvt_pk_bf16_f32 v82, v82, v83
	v_cvt_pk_bf16_f32 v83, v84, v85
	ds_write_b128 v154, v[80:83] offset:49152
	s_waitcnt lgkmcnt(1)
	v_add_f32_dpp v90, v90, v90 quad_perm:[1,0,3,2] row_mask:0xf bank_mask:0xf
	ds_read_b128 v[80:83], v153
	ds_read_b128 v[84:87], v153 offset:16
	s_waitcnt lgkmcnt(2)
	v_add_f32_dpp v90, v90, v90 quad_perm:[2,3,0,1] row_mask:0xf bank_mask:0xf
	s_waitcnt lgkmcnt(0)
	s_nop 0
	v_add_f32_dpp v90, v90, v90 row_half_mirror row_mask:0xf bank_mask:0xf
	s_waitcnt lgkmcnt(0)
	s_nop 0
	v_add_f32_dpp v90, v90, v90 row_mirror row_mask:0xf bank_mask:0xf
	v_fmamk_f32 v90, v90, 0x3c000000, v141
	v_rsq_f32_e32 v90, v90
	s_nop 0
	v_pk_mul_f32 v[94:95], v[90:91], v[124:125] op_sel_hi:[0,1]
	v_pk_mul_f32 v[80:81], v[80:81], v[94:95]
	v_pk_mul_f32 v[94:95], v[90:91], v[120:121] op_sel_hi:[0,1]
	v_pk_mul_f32 v[82:83], v[82:83], v[94:95]
	v_cvt_pk_bf16_f32 v80, v80, v81
	v_cvt_pk_bf16_f32 v81, v82, v83
	v_pk_mul_f32 v[82:83], v[90:91], v[92:93] op_sel_hi:[0,1]
	v_pk_mul_f32 v[82:83], v[84:85], v[82:83]
	v_pk_mul_f32 v[84:85], v[90:91], v[88:89] op_sel_hi:[0,1]
	v_pk_mul_f32 v[84:85], v[86:87], v[84:85]
	v_cvt_pk_bf16_f32 v82, v82, v83
	v_cvt_pk_bf16_f32 v83, v84, v85
	ds_write_b128 v154, v[80:83] offset:57344
	s_waitcnt vmcnt(1)
	ds_write_b128 v156, v[96:99] offset:16384
	s_waitcnt vmcnt(0)
	ds_write_b128 v157, v[100:103] offset:16384
	s_waitcnt lgkmcnt(0)
	s_barrier
; #define SLOAD(t) do { const size_t r0_ = (size_t)((t) * 64 + sr) * LD1 + sc; st_k0 = *(const bf16x8*)(Kh + r0_); st_k1 = *(const bf16x8*)(Kh + r0_ + (size_t)32 * LD1); \
;         st_v0 = *(const bf16x8*)(Vh + r0_); st_v1 = *(const bf16x8*)(Vh + r0_ + (size_t)32 * LD1); } while (0)
; __device__ __forceinline__ void fox_attn_unit(const Params& P, char* lds, int b, int h, int qb) {
;     ...
;         if (t - 2 > j_lo) SLOAD(t - 2);
	s_cbranch_vccnz .LBB0_1374
	v_lshl_add_u64 v[80:81], v[116:117], 0, v[112:113]
	v_add_co_u32_e32 v82, vcc, 0x11401000, v80
	s_nop 1
	v_addc_co_u32_e32 v83, vcc, 0, v81, vcc
	v_add_co_u32_e32 v84, vcc, 0x11481000, v80
	s_nop 1
	v_addc_co_u32_e32 v85, vcc, 0, v81, vcc
	global_load_dwordx4 v[108:111], v[82:83], off
	global_load_dwordx4 v[104:107], v[84:85], off
	v_add_co_u32_e32 v82, vcc, 0x11402000, v80
	s_nop 1
	v_addc_co_u32_e32 v83, vcc, 0, v81, vcc
	v_add_co_u32_e32 v80, vcc, 0x11482000, v80
	s_nop 1
	v_addc_co_u32_e32 v81, vcc, 0, v81, vcc
	global_load_dwordx4 v[96:99], v[82:83], off
	global_load_dwordx4 v[100:103], v[80:81], off

; __device__ __forceinline__ unsigned cvtpk(float lo, float hi) { f32x2_t v = {lo, hi}; bf16x2_t b = __builtin_convertvector(v, bf16x2_t); return __builtin_bit_cast(unsigned, b); }
; #define PV_RD(S, d0) do { constexpr int b_ = VB * SHM_V + v_rd_off(d0, 0, 0); \
;         TRRD(S##l0, b_); TRRD(S##h0, b_ + 2048); TRRD(S##l1, b_ + 4096); TRRD(S##h1, b_ + 6144); TRRD(S##l2, b_ + 8192); TRRD(S##h2, b_ + 10240); TRRD(S##l3, b_ + 12288); TRRD(S##h3, b_ + 14336); } while (0)
; #define PV_WAIT(n) do { asm volatile("s_waitcnt lgkmcnt(%0)" :: "i"(n) : "memory"); SBAR(); } while (0)
; template <int VB>
; __device__ __forceinline__ void pv_tile(f32x16* o, int vb0, bf16x8 pa0, bf16x8 pa1, bf16x8 pa2, bf16x8 pa3) {
;     ...
;     s16x4 Al0, Al1, Al2, Al3, Ah0, Ah1, Ah2, Ah3, Bl0, Bl1, Bl2, Bl3, Bh0, Bh1, Bh2, Bh3;
;     PV_RD(A, 0); PV_RD(B, 1); PV_WAIT(8); PV_MM(A, 0);
;     PV_RD(A, 2); PV_WAIT(8); PV_MM(B, 1);
;     PV_RD(B, 3); PV_WAIT(8); PV_MM(A, 2);
;     PV_WAIT(0); PV_MM(B, 3);
;     ...
; }
; __device__ __forceinline__ bf16x8 knorm8(bf16x8 x, const float* g) {
;     const v4u xv = __builtin_bit_cast(v4u, x); float f[8];
; #pragma unroll
;     for (int e = 0; e < 4; ++e) { f[2 * e] = __builtin_bit_cast(float, xv[e] << 16); f[2 * e + 1] = __builtin_bit_cast(float, xv[e] & 0xffff0000u); }
;     float s = 0.f;
; #pragma unroll
;     for (int e = 0; e < 8; ++e) s += f[e] * f[e];
;     s += __shfl_xor(s, 1); s += __shfl_xor(s, 2); s += __shfl_xor(s, 4); s += __shfl_xor(s, 8);
;     const float r = __builtin_amdgcn_rsqf(s * (1.0f / 128.0f) + 1e-6f);
;     const f32x4 g0 = *(const f32x4*)g, g1 = *(const f32x4*)(g + 4);
;     v4u w; w.x = cvtpk(f[0] * r * g0[0], f[1] * r * g0[1]); w.y = cvtpk(f[2] * r * g0[2], f[3] * r * g0[3]); w.z = cvtpk(f[4] * r * g1[0], f[5] * r * g1[1]); w.w = cvtpk(f[6] * r * g1[2], f[7] * r * g1[3]);
;     return __builtin_bit_cast(bf16x8, w);
; __device__ __forceinline__ void fox_attn_unit(const Params& P, char* lds, int b, int h, int qb) {
;     ...
;         { const int kb0 = (t - 1) * 64; fox_tile<1>(o, m_reg, l_reg, lds, ckl, al_l, vb0, qr, cq, qpos, kb0, kb0 + 63 > qlo, r32, hi); }
;         if (t - 2 > j_lo) SWRITE(0);
;         __syncthreads();
.LBB0_1380:
	ds_read_b64_tr_b16 v[124:125], v158 offset:0x4000
	ds_read_b64_tr_b16 v[126:127], v158 offset:0x4800
	ds_read_b64_tr_b16 v[130:131], v158 offset:0x5000
	ds_read_b64_tr_b16 v[132:133], v158 offset:0x5800
	ds_read_b64_tr_b16 v[134:135], v158 offset:0x6000
	ds_read_b64_tr_b16 v[136:137], v158 offset:0x6800
	ds_read_b64_tr_b16 v[178:179], v158 offset:0x7000
	ds_read_b64_tr_b16 v[180:181], v158 offset:0x7800
	ds_read_b64_tr_b16 v[182:183], v158 offset:0x4200
	ds_read_b64_tr_b16 v[184:185], v158 offset:0x4a00
	ds_read_b64_tr_b16 v[186:187], v158 offset:0x5200
	ds_read_b64_tr_b16 v[188:189], v158 offset:0x5a00
	ds_read_b64_tr_b16 v[190:191], v158 offset:0x6200
	ds_read_b64_tr_b16 v[192:193], v158 offset:0x6a00
	ds_read_b64_tr_b16 v[194:195], v158 offset:0x7200
	ds_read_b64_tr_b16 v[196:197], v158 offset:0x7a00
	s_waitcnt lgkmcnt(8)
	s_nop 0
	v_mfma_f32_32x32x16_bf16 v[0:15], v[80:83], v[124:127], v[0:15]
	ds_read_b64_tr_b16 v[124:125], v158 offset:0x4400
	ds_read_b64_tr_b16 v[126:127], v158 offset:0x4c00
	v_mfma_f32_32x32x16_bf16 v[0:15], v[84:87], v[130:133], v[0:15]
	ds_read_b64_tr_b16 v[130:131], v158 offset:0x5400
	ds_read_b64_tr_b16 v[132:133], v158 offset:0x5c00
	v_mfma_f32_32x32x16_bf16 v[0:15], v[88:91], v[134:137], v[0:15]
	ds_read_b64_tr_b16 v[134:135], v158 offset:0x6400
	ds_read_b64_tr_b16 v[136:137], v158 offset:0x6c00
	v_mfma_f32_32x32x16_bf16 v[0:15], v[92:95], v[178:181], v[0:15]
	ds_read_b64_tr_b16 v[178:179], v158 offset:0x7400
	ds_read_b64_tr_b16 v[180:181], v158 offset:0x7c00
	s_waitcnt lgkmcnt(8)
	v_mfma_f32_32x32x16_bf16 v[32:47], v[80:83], v[182:185], v[32:47]
	ds_read_b64_tr_b16 v[182:183], v158 offset:0x4600
	ds_read_b64_tr_b16 v[184:185], v158 offset:0x4e00
	v_mfma_f32_32x32x16_bf16 v[32:47], v[84:87], v[186:189], v[32:47]
	ds_read_b64_tr_b16 v[186:187], v158 offset:0x5600
	ds_read_b64_tr_b16 v[188:189], v158 offset:0x5e00
	v_mfma_f32_32x32x16_bf16 v[32:47], v[88:91], v[190:193], v[32:47]
	ds_read_b64_tr_b16 v[190:191], v158 offset:0x6600
	ds_read_b64_tr_b16 v[192:193], v158 offset:0x6e00
	v_mfma_f32_32x32x16_bf16 v[32:47], v[92:95], v[194:197], v[32:47]
	ds_read_b64_tr_b16 v[194:195], v158 offset:0x7600
	ds_read_b64_tr_b16 v[196:197], v158 offset:0x7e00
	s_waitcnt lgkmcnt(8)
	v_mfma_f32_32x32x16_bf16 v[48:63], v[80:83], v[124:127], v[48:63]
	s_waitcnt lgkmcnt(0)
	v_mfma_f32_32x32x16_bf16 v[48:63], v[84:87], v[130:133], v[48:63]
	v_mfma_f32_32x32x16_bf16 v[48:63], v[88:91], v[134:137], v[48:63]
	v_mfma_f32_32x32x16_bf16 v[48:63], v[92:95], v[178:181], v[48:63]
	v_mfma_f32_32x32x16_bf16 v[16:31], v[80:83], v[182:185], v[16:31]
	s_andn2_b64 vcc, exec, s[74:75]
	v_mfma_f32_32x32x16_bf16 v[16:31], v[84:87], v[186:189], v[16:31]
	v_mfma_f32_32x32x16_bf16 v[16:31], v[88:91], v[190:193], v[16:31]
	v_mfma_f32_32x32x16_bf16 v[16:31], v[92:95], v[194:197], v[16:31]
	s_cbranch_vccnz .LBB0_1365
	s_waitcnt vmcnt(3)
	v_lshlrev_b32_e32 v94, 16, v108
	v_and_b32_e32 v95, 0xffff0000, v108
	v_lshlrev_b32_e32 v92, 16, v109
	v_and_b32_e32 v93, 0xffff0000, v109
	v_pk_mul_f32 v[86:87], v[94:95], v[94:95]
	v_pk_mul_f32 v[84:85], v[92:93], v[92:93]
	v_add_f32_e32 v86, v86, v87
	v_lshlrev_b32_e32 v90, 16, v110
	v_and_b32_e32 v91, 0xffff0000, v110
	v_add_f32_e32 v84, v84, v86
	v_pk_mul_f32 v[82:83], v[90:91], v[90:91]
	v_add_f32_e32 v84, v85, v84
	v_lshlrev_b32_e32 v88, 16, v111
	v_and_b32_e32 v89, 0xffff0000, v111
	v_add_f32_e32 v82, v82, v84
	v_pk_mul_f32 v[80:81], v[88:89], v[88:89]
	v_add_f32_e32 v82, v83, v82
	v_add_f32_e32 v80, v80, v82
	v_add_f32_e32 v80, v81, v80
	s_waitcnt vmcnt(2)
	v_lshlrev_b32_e32 v126, 16, v104
	v_and_b32_e32 v127, 0xffff0000, v104
	v_lshlrev_b32_e32 v124, 16, v105
	v_and_b32_e32 v125, 0xffff0000, v105
	s_waitcnt lgkmcnt(0)
	v_add_f32_dpp v80, v80, v80 quad_perm:[1,0,3,2] row_mask:0xf bank_mask:0xf
	v_pk_mul_f32 v[86:87], v[126:127], v[126:127]
	v_lshlrev_b32_e32 v110, 16, v106
	v_and_b32_e32 v111, 0xffff0000, v106
	v_add_f32_e32 v86, v86, v87
	s_waitcnt lgkmcnt(0)
	v_add_f32_dpp v80, v80, v80 quad_perm:[2,3,0,1] row_mask:0xf bank_mask:0xf
	v_pk_mul_f32 v[82:83], v[110:111], v[110:111]
	v_lshlrev_b32_e32 v108, 16, v107
	v_and_b32_e32 v109, 0xffff0000, v107
	s_waitcnt lgkmcnt(0)
	v_add_f32_dpp v84, v80, v80 row_half_mirror row_mask:0xf bank_mask:0xf
	v_pk_mul_f32 v[80:81], v[108:109], v[108:109]
	s_waitcnt lgkmcnt(0)
	v_add_f32_dpp v84, v84, v84 row_mirror row_mask:0xf bank_mask:0xf
	v_fmamk_f32 v84, v84, 0x3c000000, v141
	v_rsq_f32_e32 v106, v84
	v_pk_mul_f32 v[84:85], v[124:125], v[124:125]
	v_pk_mul_f32 v[92:93], v[106:107], v[92:93] op_sel_hi:[0,1]
	v_add_f32_e32 v84, v84, v86
	v_add_f32_e32 v84, v85, v84
	v_add_f32_e32 v82, v82, v84
	v_add_f32_e32 v82, v83, v82
	v_add_f32_e32 v80, v80, v82
	v_add_f32_e32 v104, v81, v80
	ds_read_b128 v[80:83], v153
	ds_read_b128 v[84:87], v153 offset:16
	v_pk_mul_f32 v[94:95], v[106:107], v[94:95] op_sel_hi:[0,1]
	s_waitcnt lgkmcnt(2)
	v_add_f32_dpp v104, v104, v104 quad_perm:[1,0,3,2] row_mask:0xf bank_mask:0xf
	s_waitcnt lgkmcnt(1)
	v_pk_mul_f32 v[82:83], v[82:83], v[92:93]
	v_pk_mul_f32 v[80:81], v[80:81], v[94:95]
	s_waitcnt lgkmcnt(0)
	v_add_f32_dpp v92, v104, v104 quad_perm:[2,3,0,1] row_mask:0xf bank_mask:0xf
	v_cvt_pk_bf16_f32 v80, v80, v81
	v_cvt_pk_bf16_f32 v81, v82, v83
	v_pk_mul_f32 v[82:83], v[106:107], v[90:91] op_sel_hi:[0,1]
	v_pk_mul_f32 v[82:83], v[84:85], v[82:83]
	s_waitcnt lgkmcnt(0)
	v_add_f32_dpp v90, v92, v92 row_half_mirror row_mask:0xf bank_mask:0xf
	v_pk_mul_f32 v[84:85], v[106:107], v[88:89] op_sel_hi:[0,1]
	v_pk_mul_f32 v[84:85], v[86:87], v[84:85]
	v_cvt_pk_bf16_f32 v82, v82, v83
	v_cvt_pk_bf16_f32 v83, v84, v85
	ds_write_b128 v154, v[80:83] offset:32768
	s_waitcnt lgkmcnt(1)
	v_add_f32_dpp v80, v90, v90 row_mirror row_mask:0xf bank_mask:0xf
	v_fmamk_f32 v80, v80, 0x3c000000, v141
	v_rsq_f32_e32 v88, v80
	ds_read_b128 v[80:83], v153
	ds_read_b128 v[84:87], v153 offset:16
	v_pk_mul_f32 v[90:91], v[88:89], v[126:127] op_sel_hi:[0,1]
	s_waitcnt lgkmcnt(1)
	v_pk_mul_f32 v[80:81], v[80:81], v[90:91]
	v_pk_mul_f32 v[90:91], v[88:89], v[124:125] op_sel_hi:[0,1]
	v_pk_mul_f32 v[82:83], v[82:83], v[90:91]
	v_cvt_pk_bf16_f32 v80, v80, v81
	v_cvt_pk_bf16_f32 v81, v82, v83
	v_pk_mul_f32 v[82:83], v[88:89], v[110:111] op_sel_hi:[0,1]
	s_waitcnt lgkmcnt(0)
	v_pk_mul_f32 v[82:83], v[84:85], v[82:83]
	v_pk_mul_f32 v[84:85], v[88:89], v[108:109] op_sel_hi:[0,1]
	v_pk_mul_f32 v[84:85], v[86:87], v[84:85]
	v_cvt_pk_bf16_f32 v82, v82, v83
	v_cvt_pk_bf16_f32 v83, v84, v85
	ds_write_b128 v154, v[80:83] offset:40960
	s_waitcnt vmcnt(1)
	ds_write_b128 v156, v[96:99]
	s_waitcnt vmcnt(0)
	ds_write_b128 v157, v[100:103]
	s_branch .LBB0_1365
